# G2 fused gate GEMM: gate loads of the mid hook and epilogue issued per block (8 / 4 in flight) with counted vmcnt waits instead of one serialized round trip per column group
# speedup vs baseline: 1.0338x; 1.0102x over previous
.LBB0_1080:
	s_andn2_b64 vcc, exec, s[26:27]
	s_cbranch_vccnz .LBB0_1082
	v_mov_b32_e32 v0, v151
	s_movk_i32 s30, 0x1320
	s_nop 0
	v_mad_u64_u32 v[2:3], s[28:29], v0, s30, v[136:137]
	v_mov_b32_e32 v215, 0
	v_add_u32_e32 v214, s13, v2
	v_lshlrev_b64 v[216:217], 1, v[214:215]
	v_lshl_add_u64 v[218:219], s[4:5], 0, v[216:217]
	v_lshl_add_u64 v[220:221], s[8:9], 0, v[216:217]
	global_load_dwordx2 v[218:219], v[218:219], off
	global_load_dwordx2 v[220:221], v[220:221], off
	v_add_u32_e32 v214, s56, v2
	v_lshlrev_b64 v[216:217], 1, v[214:215]
	v_lshl_add_u64 v[222:223], s[4:5], 0, v[216:217]
	v_lshl_add_u64 v[224:225], s[8:9], 0, v[216:217]
	global_load_dwordx2 v[222:223], v[222:223], off
	global_load_dwordx2 v[224:225], v[224:225], off
	v_add_u32_e32 v214, s57, v2
	v_lshlrev_b64 v[216:217], 1, v[214:215]
	v_lshl_add_u64 v[226:227], s[4:5], 0, v[216:217]
	v_lshl_add_u64 v[228:229], s[8:9], 0, v[216:217]
	global_load_dwordx2 v[226:227], v[226:227], off
	global_load_dwordx2 v[228:229], v[228:229], off
	v_add_u32_e32 v214, s58, v2
	v_lshlrev_b64 v[216:217], 1, v[214:215]
	v_lshl_add_u64 v[230:231], s[4:5], 0, v[216:217]
	v_lshl_add_u64 v[232:233], s[8:9], 0, v[216:217]
	global_load_dwordx2 v[230:231], v[230:231], off
	global_load_dwordx2 v[232:233], v[232:233], off
	s_nop 0
	s_nop 0
	s_nop 0
	s_nop 0
	s_waitcnt vmcnt(6)
	v_lshlrev_b32_e32 v0, 16, v220
	v_mul_f32_e32 v0, 0xbfb8aa3b, v0
	v_exp_f32_e32 v0, v0
	s_nop 0
	v_min_f32_e32 v168, 0x7149f2ca, v0
	v_lshlrev_b32_e32 v0, 16, v218
	v_mul_f32_e32 v0, 0xbfb8aa3b, v0
	v_exp_f32_e32 v0, v0
	s_nop 0
	v_min_f32_e32 v0, 0x7149f2ca, v0
	v_add_f32_e32 v0, 1.0, v0
	v_rcp_f32_e32 v170, v0
	v_and_b32_e32 v0, 0xffff0000, v220
	v_mul_f32_e32 v0, 0xbfb8aa3b, v0
	v_exp_f32_e32 v0, v0
	s_nop 0
	v_min_f32_e32 v169, 0x7149f2ca, v0
	v_and_b32_e32 v0, 0xffff0000, v218
	v_mul_f32_e32 v0, 0xbfb8aa3b, v0
	v_exp_f32_e32 v0, v0
	v_pk_add_f32 v[168:169], v[168:169], 1.0 op_sel_hi:[1,0]
	v_min_f32_e32 v0, 0x7149f2ca, v0
	v_add_f32_e32 v0, 1.0, v0
	v_rcp_f32_e32 v171, v0
	v_lshlrev_b32_e32 v0, 16, v221
	v_mul_f32_e32 v0, 0xbfb8aa3b, v0
	v_exp_f32_e32 v0, v0
	v_pk_mul_f32 v[168:169], v[168:169], v[170:171]
	v_min_f32_e32 v146, 0x7149f2ca, v0
	v_lshlrev_b32_e32 v0, 16, v219
	v_mul_f32_e32 v0, 0xbfb8aa3b, v0
	v_exp_f32_e32 v0, v0
	v_pk_mul_f32 v[128:129], v[128:129], v[168:169]
	v_min_f32_e32 v0, 0x7149f2ca, v0
	v_add_f32_e32 v0, 1.0, v0
	v_rcp_f32_e32 v166, v0
	v_and_b32_e32 v0, 0xffff0000, v221
	v_mul_f32_e32 v0, 0xbfb8aa3b, v0
	v_exp_f32_e32 v0, v0
	s_nop 0
	v_min_f32_e32 v147, 0x7149f2ca, v0
	v_and_b32_e32 v0, 0xffff0000, v219
	v_mul_f32_e32 v0, 0xbfb8aa3b, v0
	v_exp_f32_e32 v0, v0
	v_pk_add_f32 v[146:147], v[146:147], 1.0 op_sel_hi:[1,0]
	v_min_f32_e32 v0, 0x7149f2ca, v0
	v_add_f32_e32 v0, 1.0, v0
	v_rcp_f32_e32 v167, v0
	s_nop 0
	v_pk_mul_f32 v[146:147], v[146:147], v[166:167]
	s_nop 0
	v_pk_mul_f32 v[130:131], v[130:131], v[146:147]
	s_nop 0
	s_nop 0
	s_nop 0
	s_waitcnt vmcnt(4)
	v_lshlrev_b32_e32 v0, 16, v224
	v_mul_f32_e32 v0, 0xbfb8aa3b, v0
	v_exp_f32_e32 v0, v0
	s_nop 0
	v_min_f32_e32 v168, 0x7149f2ca, v0
	v_lshlrev_b32_e32 v0, 16, v222
	v_mul_f32_e32 v0, 0xbfb8aa3b, v0
	v_exp_f32_e32 v0, v0
	s_nop 0
	v_min_f32_e32 v0, 0x7149f2ca, v0
	v_add_f32_e32 v0, 1.0, v0
	v_rcp_f32_e32 v170, v0
	v_and_b32_e32 v0, 0xffff0000, v224
	v_mul_f32_e32 v0, 0xbfb8aa3b, v0
	v_exp_f32_e32 v0, v0
	s_nop 0
	v_min_f32_e32 v169, 0x7149f2ca, v0
	v_and_b32_e32 v0, 0xffff0000, v222
	v_mul_f32_e32 v0, 0xbfb8aa3b, v0
	v_exp_f32_e32 v0, v0
	v_pk_add_f32 v[168:169], v[168:169], 1.0 op_sel_hi:[1,0]
	v_min_f32_e32 v0, 0x7149f2ca, v0
	v_add_f32_e32 v0, 1.0, v0
	v_rcp_f32_e32 v171, v0
	v_lshlrev_b32_e32 v0, 16, v225
	v_mul_f32_e32 v0, 0xbfb8aa3b, v0
	v_exp_f32_e32 v0, v0
	v_pk_mul_f32 v[168:169], v[168:169], v[170:171]
	v_min_f32_e32 v146, 0x7149f2ca, v0
	v_lshlrev_b32_e32 v0, 16, v223
	v_mul_f32_e32 v0, 0xbfb8aa3b, v0
	v_exp_f32_e32 v0, v0
	v_pk_mul_f32 v[124:125], v[124:125], v[168:169]
	v_min_f32_e32 v0, 0x7149f2ca, v0
	v_add_f32_e32 v0, 1.0, v0
	v_rcp_f32_e32 v166, v0
	v_and_b32_e32 v0, 0xffff0000, v225
	v_mul_f32_e32 v0, 0xbfb8aa3b, v0
	v_exp_f32_e32 v0, v0
	s_nop 0
	v_min_f32_e32 v147, 0x7149f2ca, v0
	v_and_b32_e32 v0, 0xffff0000, v223
	v_mul_f32_e32 v0, 0xbfb8aa3b, v0
	v_exp_f32_e32 v0, v0
	v_pk_add_f32 v[146:147], v[146:147], 1.0 op_sel_hi:[1,0]
	v_min_f32_e32 v0, 0x7149f2ca, v0
	v_add_f32_e32 v0, 1.0, v0
	v_rcp_f32_e32 v167, v0
	s_nop 0
	v_pk_mul_f32 v[146:147], v[146:147], v[166:167]
	s_nop 0
	v_pk_mul_f32 v[126:127], v[126:127], v[146:147]
	s_nop 0
	s_nop 0
	s_nop 0
	s_waitcnt vmcnt(2)
	v_lshlrev_b32_e32 v0, 16, v228
	v_mul_f32_e32 v0, 0xbfb8aa3b, v0
	v_exp_f32_e32 v0, v0
	s_nop 0
	v_min_f32_e32 v168, 0x7149f2ca, v0
	v_lshlrev_b32_e32 v0, 16, v226
	v_mul_f32_e32 v0, 0xbfb8aa3b, v0
	v_exp_f32_e32 v0, v0
	s_nop 0
	v_min_f32_e32 v0, 0x7149f2ca, v0
	v_add_f32_e32 v0, 1.0, v0
	v_rcp_f32_e32 v170, v0
	v_and_b32_e32 v0, 0xffff0000, v228
	v_mul_f32_e32 v0, 0xbfb8aa3b, v0
	v_exp_f32_e32 v0, v0
	s_nop 0
	v_min_f32_e32 v169, 0x7149f2ca, v0
	v_and_b32_e32 v0, 0xffff0000, v226
	v_mul_f32_e32 v0, 0xbfb8aa3b, v0
	v_exp_f32_e32 v0, v0
	v_pk_add_f32 v[168:169], v[168:169], 1.0 op_sel_hi:[1,0]
	v_min_f32_e32 v0, 0x7149f2ca, v0
	v_add_f32_e32 v0, 1.0, v0
	v_rcp_f32_e32 v171, v0
	v_lshlrev_b32_e32 v0, 16, v229
	v_mul_f32_e32 v0, 0xbfb8aa3b, v0
	v_exp_f32_e32 v0, v0
	v_pk_mul_f32 v[168:169], v[168:169], v[170:171]
	v_min_f32_e32 v146, 0x7149f2ca, v0
	v_lshlrev_b32_e32 v0, 16, v227
	v_mul_f32_e32 v0, 0xbfb8aa3b, v0
	v_exp_f32_e32 v0, v0
	v_pk_mul_f32 v[120:121], v[120:121], v[168:169]
	v_min_f32_e32 v0, 0x7149f2ca, v0
	v_add_f32_e32 v0, 1.0, v0
	v_rcp_f32_e32 v166, v0
	v_and_b32_e32 v0, 0xffff0000, v229
	v_mul_f32_e32 v0, 0xbfb8aa3b, v0
	v_exp_f32_e32 v0, v0
	s_nop 0
	v_min_f32_e32 v147, 0x7149f2ca, v0
	v_and_b32_e32 v0, 0xffff0000, v227
	v_mul_f32_e32 v0, 0xbfb8aa3b, v0
	v_exp_f32_e32 v0, v0
	v_pk_add_f32 v[146:147], v[146:147], 1.0 op_sel_hi:[1,0]
	v_min_f32_e32 v0, 0x7149f2ca, v0
	v_add_f32_e32 v0, 1.0, v0
	v_rcp_f32_e32 v167, v0
	s_nop 0
	s_nop 0
	v_pk_mul_f32 v[146:147], v[146:147], v[166:167]
	s_nop 0
	v_pk_mul_f32 v[122:123], v[122:123], v[146:147]
	s_nop 0
	s_nop 0
	s_waitcnt vmcnt(0)
	v_lshlrev_b32_e32 v0, 16, v232
	v_mul_f32_e32 v0, 0xbfb8aa3b, v0
	v_exp_f32_e32 v0, v0
	s_nop 0
	v_min_f32_e32 v166, 0x7149f2ca, v0
	v_lshlrev_b32_e32 v0, 16, v230
	v_mul_f32_e32 v0, 0xbfb8aa3b, v0
	v_exp_f32_e32 v0, v0
	s_nop 0
	v_min_f32_e32 v0, 0x7149f2ca, v0
	v_add_f32_e32 v0, 1.0, v0
	v_rcp_f32_e32 v168, v0
	v_and_b32_e32 v0, 0xffff0000, v232
	v_mul_f32_e32 v0, 0xbfb8aa3b, v0
	v_exp_f32_e32 v0, v0
	s_nop 0
	v_min_f32_e32 v167, 0x7149f2ca, v0
	v_and_b32_e32 v0, 0xffff0000, v230
	v_mul_f32_e32 v0, 0xbfb8aa3b, v0
	v_exp_f32_e32 v0, v0
	v_pk_add_f32 v[166:167], v[166:167], 1.0 op_sel_hi:[1,0]
	v_min_f32_e32 v0, 0x7149f2ca, v0
	v_add_f32_e32 v0, 1.0, v0
	v_rcp_f32_e32 v169, v0
	v_lshlrev_b32_e32 v0, 16, v233
	v_mul_f32_e32 v0, 0xbfb8aa3b, v0
	v_exp_f32_e32 v0, v0
	v_pk_mul_f32 v[166:167], v[166:167], v[168:169]
	v_min_f32_e32 v2, 0x7149f2ca, v0
	v_lshlrev_b32_e32 v0, 16, v231
	v_mul_f32_e32 v0, 0xbfb8aa3b, v0
	v_exp_f32_e32 v0, v0
	v_pk_mul_f32 v[116:117], v[116:117], v[166:167]
	v_min_f32_e32 v0, 0x7149f2ca, v0
	v_add_f32_e32 v0, 1.0, v0
	v_rcp_f32_e32 v146, v0
	v_and_b32_e32 v0, 0xffff0000, v233
	v_mul_f32_e32 v0, 0xbfb8aa3b, v0
	v_exp_f32_e32 v0, v0
	s_nop 0
	v_min_f32_e32 v3, 0x7149f2ca, v0
	v_and_b32_e32 v0, 0xffff0000, v231
	v_mul_f32_e32 v0, 0xbfb8aa3b, v0
	v_exp_f32_e32 v0, v0
	v_pk_add_f32 v[2:3], v[2:3], 1.0 op_sel_hi:[1,0]
	v_min_f32_e32 v0, 0x7149f2ca, v0
	v_add_f32_e32 v0, 1.0, v0
	v_rcp_f32_e32 v147, v0
	v_mov_b32_e32 v0, v152
	v_pk_mul_f32 v[2:3], v[2:3], v[146:147]
	s_nop 0
	v_pk_mul_f32 v[118:119], v[118:119], v[2:3]
	s_nop 0
	s_nop 0
	v_mad_u64_u32 v[2:3], s[28:29], v0, s30, v[136:137]
	v_mov_b32_e32 v215, 0
	v_add_u32_e32 v214, s13, v2
	v_lshlrev_b64 v[216:217], 1, v[214:215]
	v_lshl_add_u64 v[218:219], s[4:5], 0, v[216:217]
	v_lshl_add_u64 v[220:221], s[8:9], 0, v[216:217]
	global_load_dwordx2 v[218:219], v[218:219], off
	global_load_dwordx2 v[220:221], v[220:221], off
	v_add_u32_e32 v214, s56, v2
	v_lshlrev_b64 v[216:217], 1, v[214:215]
	v_lshl_add_u64 v[222:223], s[4:5], 0, v[216:217]
	v_lshl_add_u64 v[224:225], s[8:9], 0, v[216:217]
	global_load_dwordx2 v[222:223], v[222:223], off
	global_load_dwordx2 v[224:225], v[224:225], off
	v_add_u32_e32 v214, s57, v2
	v_lshlrev_b64 v[216:217], 1, v[214:215]
	v_lshl_add_u64 v[226:227], s[4:5], 0, v[216:217]
	v_lshl_add_u64 v[228:229], s[8:9], 0, v[216:217]
	global_load_dwordx2 v[226:227], v[226:227], off
	global_load_dwordx2 v[228:229], v[228:229], off
	v_add_u32_e32 v214, s58, v2
	v_lshlrev_b64 v[216:217], 1, v[214:215]
	v_lshl_add_u64 v[230:231], s[4:5], 0, v[216:217]
	v_lshl_add_u64 v[232:233], s[8:9], 0, v[216:217]
	global_load_dwordx2 v[230:231], v[230:231], off
	global_load_dwordx2 v[232:233], v[232:233], off
	s_nop 0
	s_nop 0
	s_nop 0
	s_nop 0
	s_waitcnt vmcnt(6)
	v_lshlrev_b32_e32 v0, 16, v220
	v_mul_f32_e32 v0, 0xbfb8aa3b, v0
	v_exp_f32_e32 v0, v0
	s_nop 0
	v_min_f32_e32 v168, 0x7149f2ca, v0
	v_lshlrev_b32_e32 v0, 16, v218
	v_mul_f32_e32 v0, 0xbfb8aa3b, v0
	v_exp_f32_e32 v0, v0
	s_nop 0
	v_min_f32_e32 v0, 0x7149f2ca, v0
	v_add_f32_e32 v0, 1.0, v0
	v_rcp_f32_e32 v170, v0
	v_and_b32_e32 v0, 0xffff0000, v220
	v_mul_f32_e32 v0, 0xbfb8aa3b, v0
	v_exp_f32_e32 v0, v0
	s_nop 0
	v_min_f32_e32 v169, 0x7149f2ca, v0
	v_and_b32_e32 v0, 0xffff0000, v218
	v_mul_f32_e32 v0, 0xbfb8aa3b, v0
	v_exp_f32_e32 v0, v0
	v_pk_add_f32 v[168:169], v[168:169], 1.0 op_sel_hi:[1,0]
	v_min_f32_e32 v0, 0x7149f2ca, v0
	v_add_f32_e32 v0, 1.0, v0
	v_rcp_f32_e32 v171, v0
	v_lshlrev_b32_e32 v0, 16, v221
	v_mul_f32_e32 v0, 0xbfb8aa3b, v0
	v_exp_f32_e32 v0, v0
	v_pk_mul_f32 v[168:169], v[168:169], v[170:171]
	v_min_f32_e32 v146, 0x7149f2ca, v0
	v_lshlrev_b32_e32 v0, 16, v219
	v_mul_f32_e32 v0, 0xbfb8aa3b, v0
	v_exp_f32_e32 v0, v0
	v_pk_mul_f32 v[112:113], v[112:113], v[168:169]
	v_min_f32_e32 v0, 0x7149f2ca, v0
	v_add_f32_e32 v0, 1.0, v0
	v_rcp_f32_e32 v166, v0
	v_and_b32_e32 v0, 0xffff0000, v221
	v_mul_f32_e32 v0, 0xbfb8aa3b, v0
	v_exp_f32_e32 v0, v0
	s_nop 0
	v_min_f32_e32 v147, 0x7149f2ca, v0
	v_and_b32_e32 v0, 0xffff0000, v219
	v_mul_f32_e32 v0, 0xbfb8aa3b, v0
	v_exp_f32_e32 v0, v0
	v_pk_add_f32 v[146:147], v[146:147], 1.0 op_sel_hi:[1,0]
	v_min_f32_e32 v0, 0x7149f2ca, v0
	v_add_f32_e32 v0, 1.0, v0
	v_rcp_f32_e32 v167, v0
	s_nop 0
	v_pk_mul_f32 v[146:147], v[146:147], v[166:167]
	s_nop 0
	v_pk_mul_f32 v[114:115], v[114:115], v[146:147]
	s_nop 0
	s_nop 0
	s_nop 0
	s_waitcnt vmcnt(4)
	v_lshlrev_b32_e32 v0, 16, v224
	v_mul_f32_e32 v0, 0xbfb8aa3b, v0
	v_exp_f32_e32 v0, v0
	s_nop 0
	v_min_f32_e32 v168, 0x7149f2ca, v0
	v_lshlrev_b32_e32 v0, 16, v222
	v_mul_f32_e32 v0, 0xbfb8aa3b, v0
	v_exp_f32_e32 v0, v0
	s_nop 0
	v_min_f32_e32 v0, 0x7149f2ca, v0
	v_add_f32_e32 v0, 1.0, v0
	v_rcp_f32_e32 v170, v0
	v_and_b32_e32 v0, 0xffff0000, v224
	v_mul_f32_e32 v0, 0xbfb8aa3b, v0
	v_exp_f32_e32 v0, v0
	s_nop 0
	v_min_f32_e32 v169, 0x7149f2ca, v0
	v_and_b32_e32 v0, 0xffff0000, v222
	v_mul_f32_e32 v0, 0xbfb8aa3b, v0
	v_exp_f32_e32 v0, v0
	v_pk_add_f32 v[168:169], v[168:169], 1.0 op_sel_hi:[1,0]
	v_min_f32_e32 v0, 0x7149f2ca, v0
	v_add_f32_e32 v0, 1.0, v0
	v_rcp_f32_e32 v171, v0
	v_lshlrev_b32_e32 v0, 16, v225
	v_mul_f32_e32 v0, 0xbfb8aa3b, v0
	v_exp_f32_e32 v0, v0
	v_pk_mul_f32 v[168:169], v[168:169], v[170:171]
	v_min_f32_e32 v146, 0x7149f2ca, v0
	v_lshlrev_b32_e32 v0, 16, v223
	v_mul_f32_e32 v0, 0xbfb8aa3b, v0
	v_exp_f32_e32 v0, v0
	v_pk_mul_f32 v[108:109], v[108:109], v[168:169]
	v_min_f32_e32 v0, 0x7149f2ca, v0
	v_add_f32_e32 v0, 1.0, v0
	v_rcp_f32_e32 v166, v0
	v_and_b32_e32 v0, 0xffff0000, v225
	v_mul_f32_e32 v0, 0xbfb8aa3b, v0
	v_exp_f32_e32 v0, v0
	s_nop 0
	v_min_f32_e32 v147, 0x7149f2ca, v0
	v_and_b32_e32 v0, 0xffff0000, v223
	v_mul_f32_e32 v0, 0xbfb8aa3b, v0
	v_exp_f32_e32 v0, v0
	v_pk_add_f32 v[146:147], v[146:147], 1.0 op_sel_hi:[1,0]
	v_min_f32_e32 v0, 0x7149f2ca, v0
	v_add_f32_e32 v0, 1.0, v0
	v_rcp_f32_e32 v167, v0
	s_nop 0
	v_pk_mul_f32 v[146:147], v[146:147], v[166:167]
	s_nop 0
	v_pk_mul_f32 v[110:111], v[110:111], v[146:147]
	s_nop 0
	s_nop 0
	s_nop 0
	s_waitcnt vmcnt(2)
	v_lshlrev_b32_e32 v0, 16, v228
	v_mul_f32_e32 v0, 0xbfb8aa3b, v0
	v_exp_f32_e32 v0, v0
	s_nop 0
	v_min_f32_e32 v168, 0x7149f2ca, v0
	v_lshlrev_b32_e32 v0, 16, v226
	v_mul_f32_e32 v0, 0xbfb8aa3b, v0
	v_exp_f32_e32 v0, v0
	s_nop 0
	v_min_f32_e32 v0, 0x7149f2ca, v0
	v_add_f32_e32 v0, 1.0, v0
	v_rcp_f32_e32 v170, v0
	v_and_b32_e32 v0, 0xffff0000, v228
	v_mul_f32_e32 v0, 0xbfb8aa3b, v0
	v_exp_f32_e32 v0, v0
	s_nop 0
	v_min_f32_e32 v169, 0x7149f2ca, v0
	v_and_b32_e32 v0, 0xffff0000, v226
	v_mul_f32_e32 v0, 0xbfb8aa3b, v0
	v_exp_f32_e32 v0, v0
	v_pk_add_f32 v[168:169], v[168:169], 1.0 op_sel_hi:[1,0]
	v_min_f32_e32 v0, 0x7149f2ca, v0
	v_add_f32_e32 v0, 1.0, v0
	v_rcp_f32_e32 v171, v0
	v_lshlrev_b32_e32 v0, 16, v229
	v_mul_f32_e32 v0, 0xbfb8aa3b, v0
	v_exp_f32_e32 v0, v0
	v_pk_mul_f32 v[168:169], v[168:169], v[170:171]
	v_min_f32_e32 v146, 0x7149f2ca, v0
	v_lshlrev_b32_e32 v0, 16, v227
	v_mul_f32_e32 v0, 0xbfb8aa3b, v0
	v_exp_f32_e32 v0, v0
	v_pk_mul_f32 v[104:105], v[104:105], v[168:169]
	v_min_f32_e32 v0, 0x7149f2ca, v0
	v_add_f32_e32 v0, 1.0, v0
	v_rcp_f32_e32 v166, v0
	v_and_b32_e32 v0, 0xffff0000, v229
	v_mul_f32_e32 v0, 0xbfb8aa3b, v0
	v_exp_f32_e32 v0, v0
	s_nop 0
	v_min_f32_e32 v147, 0x7149f2ca, v0
	v_and_b32_e32 v0, 0xffff0000, v227
	v_mul_f32_e32 v0, 0xbfb8aa3b, v0
	v_exp_f32_e32 v0, v0
	v_pk_add_f32 v[146:147], v[146:147], 1.0 op_sel_hi:[1,0]
	v_min_f32_e32 v0, 0x7149f2ca, v0
	v_add_f32_e32 v0, 1.0, v0
	v_rcp_f32_e32 v167, v0
	s_nop 0
	s_nop 0
	v_pk_mul_f32 v[146:147], v[146:147], v[166:167]
	s_nop 0
	v_pk_mul_f32 v[106:107], v[106:107], v[146:147]
	s_nop 0
	s_nop 0
	s_waitcnt vmcnt(0)
	v_lshlrev_b32_e32 v0, 16, v232
	v_mul_f32_e32 v0, 0xbfb8aa3b, v0
	v_exp_f32_e32 v0, v0
	s_nop 0
	v_min_f32_e32 v166, 0x7149f2ca, v0
	v_lshlrev_b32_e32 v0, 16, v230
	v_mul_f32_e32 v0, 0xbfb8aa3b, v0
	v_exp_f32_e32 v0, v0
	s_nop 0
	v_min_f32_e32 v0, 0x7149f2ca, v0
	v_add_f32_e32 v0, 1.0, v0
	v_rcp_f32_e32 v168, v0
	v_and_b32_e32 v0, 0xffff0000, v232
	v_mul_f32_e32 v0, 0xbfb8aa3b, v0
	v_exp_f32_e32 v0, v0
	s_nop 0
	v_min_f32_e32 v167, 0x7149f2ca, v0
	v_and_b32_e32 v0, 0xffff0000, v230
	v_mul_f32_e32 v0, 0xbfb8aa3b, v0
	v_exp_f32_e32 v0, v0
	v_pk_add_f32 v[166:167], v[166:167], 1.0 op_sel_hi:[1,0]
	v_min_f32_e32 v0, 0x7149f2ca, v0
	v_add_f32_e32 v0, 1.0, v0
	v_rcp_f32_e32 v169, v0
	v_lshlrev_b32_e32 v0, 16, v233
	v_mul_f32_e32 v0, 0xbfb8aa3b, v0
	v_exp_f32_e32 v0, v0
	v_pk_mul_f32 v[166:167], v[166:167], v[168:169]
	v_min_f32_e32 v2, 0x7149f2ca, v0
	v_lshlrev_b32_e32 v0, 16, v231
	v_mul_f32_e32 v0, 0xbfb8aa3b, v0
	v_exp_f32_e32 v0, v0
	v_pk_mul_f32 v[100:101], v[100:101], v[166:167]
	v_min_f32_e32 v0, 0x7149f2ca, v0
	v_add_f32_e32 v0, 1.0, v0
	v_rcp_f32_e32 v146, v0
	v_and_b32_e32 v0, 0xffff0000, v233
	v_mul_f32_e32 v0, 0xbfb8aa3b, v0
	v_exp_f32_e32 v0, v0
	s_nop 0
	v_min_f32_e32 v3, 0x7149f2ca, v0
	v_and_b32_e32 v0, 0xffff0000, v231
	v_mul_f32_e32 v0, 0xbfb8aa3b, v0
	v_exp_f32_e32 v0, v0
	v_pk_add_f32 v[2:3], v[2:3], 1.0 op_sel_hi:[1,0]
	v_min_f32_e32 v0, 0x7149f2ca, v0
	v_add_f32_e32 v0, 1.0, v0
	v_rcp_f32_e32 v147, v0
	v_mov_b32_e32 v0, v153
	v_pk_mul_f32 v[2:3], v[2:3], v[146:147]
	s_nop 0
	v_pk_mul_f32 v[102:103], v[102:103], v[2:3]
	s_nop 0
	s_nop 0
	v_mad_u64_u32 v[2:3], s[28:29], v0, s30, v[136:137]
	v_mov_b32_e32 v215, 0
	v_add_u32_e32 v214, s13, v2
	v_lshlrev_b64 v[216:217], 1, v[214:215]
	v_lshl_add_u64 v[218:219], s[4:5], 0, v[216:217]
	v_lshl_add_u64 v[220:221], s[8:9], 0, v[216:217]
	global_load_dwordx2 v[218:219], v[218:219], off
	global_load_dwordx2 v[220:221], v[220:221], off
	v_add_u32_e32 v214, s56, v2
	v_lshlrev_b64 v[216:217], 1, v[214:215]
	v_lshl_add_u64 v[222:223], s[4:5], 0, v[216:217]
	v_lshl_add_u64 v[224:225], s[8:9], 0, v[216:217]
	global_load_dwordx2 v[222:223], v[222:223], off
	global_load_dwordx2 v[224:225], v[224:225], off
	v_add_u32_e32 v214, s57, v2
	v_lshlrev_b64 v[216:217], 1, v[214:215]
	v_lshl_add_u64 v[226:227], s[4:5], 0, v[216:217]
	v_lshl_add_u64 v[228:229], s[8:9], 0, v[216:217]
	global_load_dwordx2 v[226:227], v[226:227], off
	global_load_dwordx2 v[228:229], v[228:229], off
	v_add_u32_e32 v214, s58, v2
	v_lshlrev_b64 v[216:217], 1, v[214:215]
	v_lshl_add_u64 v[230:231], s[4:5], 0, v[216:217]
	v_lshl_add_u64 v[232:233], s[8:9], 0, v[216:217]
	global_load_dwordx2 v[230:231], v[230:231], off
	global_load_dwordx2 v[232:233], v[232:233], off
	s_nop 0
	s_nop 0
	s_nop 0
	s_nop 0
	s_waitcnt vmcnt(6)
	v_lshlrev_b32_e32 v0, 16, v220
	v_mul_f32_e32 v0, 0xbfb8aa3b, v0
	v_exp_f32_e32 v0, v0
	s_nop 0
	v_min_f32_e32 v168, 0x7149f2ca, v0
	v_lshlrev_b32_e32 v0, 16, v218
	v_mul_f32_e32 v0, 0xbfb8aa3b, v0
	v_exp_f32_e32 v0, v0
	s_nop 0
	v_min_f32_e32 v0, 0x7149f2ca, v0
	v_add_f32_e32 v0, 1.0, v0
	v_rcp_f32_e32 v170, v0
	v_and_b32_e32 v0, 0xffff0000, v220
	v_mul_f32_e32 v0, 0xbfb8aa3b, v0
	v_exp_f32_e32 v0, v0
	s_nop 0
	v_min_f32_e32 v169, 0x7149f2ca, v0
	v_and_b32_e32 v0, 0xffff0000, v218
	v_mul_f32_e32 v0, 0xbfb8aa3b, v0
	v_exp_f32_e32 v0, v0
	v_pk_add_f32 v[168:169], v[168:169], 1.0 op_sel_hi:[1,0]
	v_min_f32_e32 v0, 0x7149f2ca, v0
	v_add_f32_e32 v0, 1.0, v0
	v_rcp_f32_e32 v171, v0
	v_lshlrev_b32_e32 v0, 16, v221
	v_mul_f32_e32 v0, 0xbfb8aa3b, v0
	v_exp_f32_e32 v0, v0
	v_pk_mul_f32 v[168:169], v[168:169], v[170:171]
	v_min_f32_e32 v146, 0x7149f2ca, v0
	v_lshlrev_b32_e32 v0, 16, v219
	v_mul_f32_e32 v0, 0xbfb8aa3b, v0
	v_exp_f32_e32 v0, v0
	v_pk_mul_f32 v[96:97], v[96:97], v[168:169]
	v_min_f32_e32 v0, 0x7149f2ca, v0
	v_add_f32_e32 v0, 1.0, v0
	v_rcp_f32_e32 v166, v0
	v_and_b32_e32 v0, 0xffff0000, v221
	v_mul_f32_e32 v0, 0xbfb8aa3b, v0
	v_exp_f32_e32 v0, v0
	s_nop 0
	v_min_f32_e32 v147, 0x7149f2ca, v0
	v_and_b32_e32 v0, 0xffff0000, v219
	v_mul_f32_e32 v0, 0xbfb8aa3b, v0
	v_exp_f32_e32 v0, v0
	v_pk_add_f32 v[146:147], v[146:147], 1.0 op_sel_hi:[1,0]
	v_min_f32_e32 v0, 0x7149f2ca, v0
	v_add_f32_e32 v0, 1.0, v0
	v_rcp_f32_e32 v167, v0
	s_nop 0
	v_pk_mul_f32 v[146:147], v[146:147], v[166:167]
	s_nop 0
	v_pk_mul_f32 v[98:99], v[98:99], v[146:147]
	s_nop 0
	s_nop 0
	s_nop 0
	s_waitcnt vmcnt(4)
	v_lshlrev_b32_e32 v0, 16, v224
	v_mul_f32_e32 v0, 0xbfb8aa3b, v0
	v_exp_f32_e32 v0, v0
	s_nop 0
	v_min_f32_e32 v168, 0x7149f2ca, v0
	v_lshlrev_b32_e32 v0, 16, v222
	v_mul_f32_e32 v0, 0xbfb8aa3b, v0
	v_exp_f32_e32 v0, v0
	s_nop 0
	v_min_f32_e32 v0, 0x7149f2ca, v0
	v_add_f32_e32 v0, 1.0, v0
	v_rcp_f32_e32 v170, v0
	v_and_b32_e32 v0, 0xffff0000, v224
	v_mul_f32_e32 v0, 0xbfb8aa3b, v0
	v_exp_f32_e32 v0, v0
	s_nop 0
	v_min_f32_e32 v169, 0x7149f2ca, v0
	v_and_b32_e32 v0, 0xffff0000, v222
	v_mul_f32_e32 v0, 0xbfb8aa3b, v0
	v_exp_f32_e32 v0, v0
	v_pk_add_f32 v[168:169], v[168:169], 1.0 op_sel_hi:[1,0]
	v_min_f32_e32 v0, 0x7149f2ca, v0
	v_add_f32_e32 v0, 1.0, v0
	v_rcp_f32_e32 v171, v0
	v_lshlrev_b32_e32 v0, 16, v225
	v_mul_f32_e32 v0, 0xbfb8aa3b, v0
	v_exp_f32_e32 v0, v0
	v_pk_mul_f32 v[168:169], v[168:169], v[170:171]
	v_min_f32_e32 v146, 0x7149f2ca, v0
	v_lshlrev_b32_e32 v0, 16, v223
	v_mul_f32_e32 v0, 0xbfb8aa3b, v0
	v_exp_f32_e32 v0, v0
	v_pk_mul_f32 v[92:93], v[92:93], v[168:169]
	v_min_f32_e32 v0, 0x7149f2ca, v0
	v_add_f32_e32 v0, 1.0, v0
	v_rcp_f32_e32 v166, v0
	v_and_b32_e32 v0, 0xffff0000, v225
	v_mul_f32_e32 v0, 0xbfb8aa3b, v0
	v_exp_f32_e32 v0, v0
	s_nop 0
	v_min_f32_e32 v147, 0x7149f2ca, v0
	v_and_b32_e32 v0, 0xffff0000, v223
	v_mul_f32_e32 v0, 0xbfb8aa3b, v0
	v_exp_f32_e32 v0, v0
	v_pk_add_f32 v[146:147], v[146:147], 1.0 op_sel_hi:[1,0]
	v_min_f32_e32 v0, 0x7149f2ca, v0
	v_add_f32_e32 v0, 1.0, v0
	v_rcp_f32_e32 v167, v0
	s_nop 0
	v_pk_mul_f32 v[146:147], v[146:147], v[166:167]
	s_nop 0
	v_pk_mul_f32 v[94:95], v[94:95], v[146:147]
	s_nop 0
	s_nop 0
	s_nop 0
	s_waitcnt vmcnt(2)
	v_lshlrev_b32_e32 v0, 16, v228
	v_mul_f32_e32 v0, 0xbfb8aa3b, v0
	v_exp_f32_e32 v0, v0
	s_nop 0
	v_min_f32_e32 v168, 0x7149f2ca, v0
	v_lshlrev_b32_e32 v0, 16, v226
	v_mul_f32_e32 v0, 0xbfb8aa3b, v0
	v_exp_f32_e32 v0, v0
	s_nop 0
	v_min_f32_e32 v0, 0x7149f2ca, v0
	v_add_f32_e32 v0, 1.0, v0
	v_rcp_f32_e32 v170, v0
	v_and_b32_e32 v0, 0xffff0000, v228
	v_mul_f32_e32 v0, 0xbfb8aa3b, v0
	v_exp_f32_e32 v0, v0
	s_nop 0
	v_min_f32_e32 v169, 0x7149f2ca, v0
	v_and_b32_e32 v0, 0xffff0000, v226
	v_mul_f32_e32 v0, 0xbfb8aa3b, v0
	v_exp_f32_e32 v0, v0
	v_pk_add_f32 v[168:169], v[168:169], 1.0 op_sel_hi:[1,0]
	v_min_f32_e32 v0, 0x7149f2ca, v0
	v_add_f32_e32 v0, 1.0, v0
	v_rcp_f32_e32 v171, v0
	v_lshlrev_b32_e32 v0, 16, v229
	v_mul_f32_e32 v0, 0xbfb8aa3b, v0
	v_exp_f32_e32 v0, v0
	v_pk_mul_f32 v[168:169], v[168:169], v[170:171]
	v_min_f32_e32 v146, 0x7149f2ca, v0
	v_lshlrev_b32_e32 v0, 16, v227
	v_mul_f32_e32 v0, 0xbfb8aa3b, v0
	v_exp_f32_e32 v0, v0
	v_pk_mul_f32 v[88:89], v[88:89], v[168:169]
	v_min_f32_e32 v0, 0x7149f2ca, v0
	v_add_f32_e32 v0, 1.0, v0
	v_rcp_f32_e32 v166, v0
	v_and_b32_e32 v0, 0xffff0000, v229
	v_mul_f32_e32 v0, 0xbfb8aa3b, v0
	v_exp_f32_e32 v0, v0
	s_nop 0
	v_min_f32_e32 v147, 0x7149f2ca, v0
	v_and_b32_e32 v0, 0xffff0000, v227
	v_mul_f32_e32 v0, 0xbfb8aa3b, v0
	v_exp_f32_e32 v0, v0
	v_pk_add_f32 v[146:147], v[146:147], 1.0 op_sel_hi:[1,0]
	v_min_f32_e32 v0, 0x7149f2ca, v0
	v_add_f32_e32 v0, 1.0, v0
	v_rcp_f32_e32 v167, v0
	s_nop 0
	s_nop 0
	v_pk_mul_f32 v[146:147], v[146:147], v[166:167]
	s_nop 0
	v_pk_mul_f32 v[90:91], v[90:91], v[146:147]
	s_nop 0
	s_nop 0
	s_waitcnt vmcnt(0)
	v_lshlrev_b32_e32 v0, 16, v232
	v_mul_f32_e32 v0, 0xbfb8aa3b, v0
	v_exp_f32_e32 v0, v0
	s_nop 0
	v_min_f32_e32 v166, 0x7149f2ca, v0
	v_lshlrev_b32_e32 v0, 16, v230
	v_mul_f32_e32 v0, 0xbfb8aa3b, v0
	v_exp_f32_e32 v0, v0
	s_nop 0
	v_min_f32_e32 v0, 0x7149f2ca, v0
	v_add_f32_e32 v0, 1.0, v0
	v_rcp_f32_e32 v168, v0
	v_and_b32_e32 v0, 0xffff0000, v232
	v_mul_f32_e32 v0, 0xbfb8aa3b, v0
	v_exp_f32_e32 v0, v0
	s_nop 0
	v_min_f32_e32 v167, 0x7149f2ca, v0
	v_and_b32_e32 v0, 0xffff0000, v230
	v_mul_f32_e32 v0, 0xbfb8aa3b, v0
	v_exp_f32_e32 v0, v0
	v_pk_add_f32 v[166:167], v[166:167], 1.0 op_sel_hi:[1,0]
	v_min_f32_e32 v0, 0x7149f2ca, v0
	v_add_f32_e32 v0, 1.0, v0
	v_rcp_f32_e32 v169, v0
	v_lshlrev_b32_e32 v0, 16, v233
	v_mul_f32_e32 v0, 0xbfb8aa3b, v0
	v_exp_f32_e32 v0, v0
	v_pk_mul_f32 v[166:167], v[166:167], v[168:169]
	v_min_f32_e32 v2, 0x7149f2ca, v0
	v_lshlrev_b32_e32 v0, 16, v231
	v_mul_f32_e32 v0, 0xbfb8aa3b, v0
	v_exp_f32_e32 v0, v0
	v_pk_mul_f32 v[84:85], v[84:85], v[166:167]
	v_min_f32_e32 v0, 0x7149f2ca, v0
	v_add_f32_e32 v0, 1.0, v0
	v_rcp_f32_e32 v146, v0
	v_and_b32_e32 v0, 0xffff0000, v233
	v_mul_f32_e32 v0, 0xbfb8aa3b, v0
	v_exp_f32_e32 v0, v0
	s_nop 0
	v_min_f32_e32 v3, 0x7149f2ca, v0
	v_and_b32_e32 v0, 0xffff0000, v231
	v_mul_f32_e32 v0, 0xbfb8aa3b, v0
	v_exp_f32_e32 v0, v0
	v_pk_add_f32 v[2:3], v[2:3], 1.0 op_sel_hi:[1,0]
	v_min_f32_e32 v0, 0x7149f2ca, v0
	v_add_f32_e32 v0, 1.0, v0
	v_rcp_f32_e32 v147, v0
	v_mov_b32_e32 v0, v154
	v_pk_mul_f32 v[2:3], v[2:3], v[146:147]
	s_nop 0
	v_pk_mul_f32 v[86:87], v[86:87], v[2:3]
	s_nop 0
	s_nop 0
	v_mad_u64_u32 v[2:3], s[28:29], v0, s30, v[136:137]
	v_mov_b32_e32 v215, 0
	v_add_u32_e32 v214, s13, v2
	v_lshlrev_b64 v[216:217], 1, v[214:215]
	v_lshl_add_u64 v[218:219], s[4:5], 0, v[216:217]
	v_lshl_add_u64 v[220:221], s[8:9], 0, v[216:217]
	global_load_dwordx2 v[218:219], v[218:219], off
	global_load_dwordx2 v[220:221], v[220:221], off
	v_add_u32_e32 v214, s56, v2
	v_lshlrev_b64 v[216:217], 1, v[214:215]
	v_lshl_add_u64 v[222:223], s[4:5], 0, v[216:217]
	v_lshl_add_u64 v[224:225], s[8:9], 0, v[216:217]
	global_load_dwordx2 v[222:223], v[222:223], off
	global_load_dwordx2 v[224:225], v[224:225], off
	v_add_u32_e32 v214, s57, v2
	v_lshlrev_b64 v[216:217], 1, v[214:215]
	v_lshl_add_u64 v[226:227], s[4:5], 0, v[216:217]
	v_lshl_add_u64 v[228:229], s[8:9], 0, v[216:217]
	global_load_dwordx2 v[226:227], v[226:227], off
	global_load_dwordx2 v[228:229], v[228:229], off
	v_add_u32_e32 v214, s58, v2
	v_lshlrev_b64 v[216:217], 1, v[214:215]
	v_lshl_add_u64 v[230:231], s[4:5], 0, v[216:217]
	v_lshl_add_u64 v[232:233], s[8:9], 0, v[216:217]
	global_load_dwordx2 v[230:231], v[230:231], off
	global_load_dwordx2 v[232:233], v[232:233], off
	s_nop 0
	s_nop 0
	s_nop 0
	s_nop 0
	s_waitcnt vmcnt(6)
	v_lshlrev_b32_e32 v0, 16, v220
	v_mul_f32_e32 v0, 0xbfb8aa3b, v0
	v_exp_f32_e32 v0, v0
	s_nop 0
	v_min_f32_e32 v168, 0x7149f2ca, v0
	v_lshlrev_b32_e32 v0, 16, v218
	v_mul_f32_e32 v0, 0xbfb8aa3b, v0
	v_exp_f32_e32 v0, v0
	s_nop 0
	v_min_f32_e32 v0, 0x7149f2ca, v0
	v_add_f32_e32 v0, 1.0, v0
	v_rcp_f32_e32 v170, v0
	v_and_b32_e32 v0, 0xffff0000, v220
	v_mul_f32_e32 v0, 0xbfb8aa3b, v0
	v_exp_f32_e32 v0, v0
	s_nop 0
	v_min_f32_e32 v169, 0x7149f2ca, v0
	v_and_b32_e32 v0, 0xffff0000, v218
	v_mul_f32_e32 v0, 0xbfb8aa3b, v0
	v_exp_f32_e32 v0, v0
	v_pk_add_f32 v[168:169], v[168:169], 1.0 op_sel_hi:[1,0]
	v_min_f32_e32 v0, 0x7149f2ca, v0
	v_add_f32_e32 v0, 1.0, v0
	v_rcp_f32_e32 v171, v0
	v_lshlrev_b32_e32 v0, 16, v221
	v_mul_f32_e32 v0, 0xbfb8aa3b, v0
	v_exp_f32_e32 v0, v0
	v_pk_mul_f32 v[168:169], v[168:169], v[170:171]
	v_min_f32_e32 v146, 0x7149f2ca, v0
	v_lshlrev_b32_e32 v0, 16, v219
	v_mul_f32_e32 v0, 0xbfb8aa3b, v0
	v_exp_f32_e32 v0, v0
	v_pk_mul_f32 v[80:81], v[80:81], v[168:169]
	v_min_f32_e32 v0, 0x7149f2ca, v0
	v_add_f32_e32 v0, 1.0, v0
	v_rcp_f32_e32 v166, v0
	v_and_b32_e32 v0, 0xffff0000, v221
	v_mul_f32_e32 v0, 0xbfb8aa3b, v0
	v_exp_f32_e32 v0, v0
	s_nop 0
	v_min_f32_e32 v147, 0x7149f2ca, v0
	v_and_b32_e32 v0, 0xffff0000, v219
	v_mul_f32_e32 v0, 0xbfb8aa3b, v0
	v_exp_f32_e32 v0, v0
	v_pk_add_f32 v[146:147], v[146:147], 1.0 op_sel_hi:[1,0]
	v_min_f32_e32 v0, 0x7149f2ca, v0
	v_add_f32_e32 v0, 1.0, v0
	v_rcp_f32_e32 v167, v0
	s_nop 0
	v_pk_mul_f32 v[146:147], v[146:147], v[166:167]
	s_nop 0
	v_pk_mul_f32 v[82:83], v[82:83], v[146:147]
	s_nop 0
	s_nop 0
	s_nop 0
	s_waitcnt vmcnt(4)
	v_lshlrev_b32_e32 v0, 16, v224
	v_mul_f32_e32 v0, 0xbfb8aa3b, v0
	v_exp_f32_e32 v0, v0
	s_nop 0
	v_min_f32_e32 v168, 0x7149f2ca, v0
	v_lshlrev_b32_e32 v0, 16, v222
	v_mul_f32_e32 v0, 0xbfb8aa3b, v0
	v_exp_f32_e32 v0, v0
	s_nop 0
	v_min_f32_e32 v0, 0x7149f2ca, v0
	v_add_f32_e32 v0, 1.0, v0
	v_rcp_f32_e32 v170, v0
	v_and_b32_e32 v0, 0xffff0000, v224
	v_mul_f32_e32 v0, 0xbfb8aa3b, v0
	v_exp_f32_e32 v0, v0
	s_nop 0
	v_min_f32_e32 v169, 0x7149f2ca, v0
	v_and_b32_e32 v0, 0xffff0000, v222
	v_mul_f32_e32 v0, 0xbfb8aa3b, v0
	v_exp_f32_e32 v0, v0
	v_pk_add_f32 v[168:169], v[168:169], 1.0 op_sel_hi:[1,0]
	v_min_f32_e32 v0, 0x7149f2ca, v0
	v_add_f32_e32 v0, 1.0, v0
	v_rcp_f32_e32 v171, v0
	v_lshlrev_b32_e32 v0, 16, v225
	v_mul_f32_e32 v0, 0xbfb8aa3b, v0
	v_exp_f32_e32 v0, v0
	v_pk_mul_f32 v[168:169], v[168:169], v[170:171]
	v_min_f32_e32 v146, 0x7149f2ca, v0
	v_lshlrev_b32_e32 v0, 16, v223
	v_mul_f32_e32 v0, 0xbfb8aa3b, v0
	v_exp_f32_e32 v0, v0
	v_pk_mul_f32 v[76:77], v[76:77], v[168:169]
	v_min_f32_e32 v0, 0x7149f2ca, v0
	v_add_f32_e32 v0, 1.0, v0
	v_rcp_f32_e32 v166, v0
	v_and_b32_e32 v0, 0xffff0000, v225
	v_mul_f32_e32 v0, 0xbfb8aa3b, v0
	v_exp_f32_e32 v0, v0
	s_nop 0
	v_min_f32_e32 v147, 0x7149f2ca, v0
	v_and_b32_e32 v0, 0xffff0000, v223
	v_mul_f32_e32 v0, 0xbfb8aa3b, v0
	v_exp_f32_e32 v0, v0
	v_pk_add_f32 v[146:147], v[146:147], 1.0 op_sel_hi:[1,0]
	v_min_f32_e32 v0, 0x7149f2ca, v0
	v_add_f32_e32 v0, 1.0, v0
	v_rcp_f32_e32 v167, v0
	s_nop 0
	v_pk_mul_f32 v[146:147], v[146:147], v[166:167]
	s_nop 0
	v_pk_mul_f32 v[78:79], v[78:79], v[146:147]
	s_nop 0
	s_nop 0
	s_nop 0
	s_waitcnt vmcnt(2)
	v_lshlrev_b32_e32 v0, 16, v228
	v_mul_f32_e32 v0, 0xbfb8aa3b, v0
	v_exp_f32_e32 v0, v0
	s_nop 0
	v_min_f32_e32 v168, 0x7149f2ca, v0
	v_lshlrev_b32_e32 v0, 16, v226
	v_mul_f32_e32 v0, 0xbfb8aa3b, v0
	v_exp_f32_e32 v0, v0
	s_nop 0
	v_min_f32_e32 v0, 0x7149f2ca, v0
	v_add_f32_e32 v0, 1.0, v0
	v_rcp_f32_e32 v170, v0
	v_and_b32_e32 v0, 0xffff0000, v228
	v_mul_f32_e32 v0, 0xbfb8aa3b, v0
	v_exp_f32_e32 v0, v0
	s_nop 0
	v_min_f32_e32 v169, 0x7149f2ca, v0
	v_and_b32_e32 v0, 0xffff0000, v226
	v_mul_f32_e32 v0, 0xbfb8aa3b, v0
	v_exp_f32_e32 v0, v0
	v_pk_add_f32 v[168:169], v[168:169], 1.0 op_sel_hi:[1,0]
	v_min_f32_e32 v0, 0x7149f2ca, v0
	v_add_f32_e32 v0, 1.0, v0
	v_rcp_f32_e32 v171, v0
	v_lshlrev_b32_e32 v0, 16, v229
	v_mul_f32_e32 v0, 0xbfb8aa3b, v0
	v_exp_f32_e32 v0, v0
	v_pk_mul_f32 v[168:169], v[168:169], v[170:171]
	v_min_f32_e32 v146, 0x7149f2ca, v0
	v_lshlrev_b32_e32 v0, 16, v227
	v_mul_f32_e32 v0, 0xbfb8aa3b, v0
	v_exp_f32_e32 v0, v0
	v_pk_mul_f32 v[72:73], v[72:73], v[168:169]
	v_min_f32_e32 v0, 0x7149f2ca, v0
	v_add_f32_e32 v0, 1.0, v0
	v_rcp_f32_e32 v166, v0
	v_and_b32_e32 v0, 0xffff0000, v229
	v_mul_f32_e32 v0, 0xbfb8aa3b, v0
	v_exp_f32_e32 v0, v0
	s_nop 0
	v_min_f32_e32 v147, 0x7149f2ca, v0
	v_and_b32_e32 v0, 0xffff0000, v227
	v_mul_f32_e32 v0, 0xbfb8aa3b, v0
	v_exp_f32_e32 v0, v0
	v_pk_add_f32 v[146:147], v[146:147], 1.0 op_sel_hi:[1,0]
	v_min_f32_e32 v0, 0x7149f2ca, v0
	v_add_f32_e32 v0, 1.0, v0
	v_rcp_f32_e32 v167, v0
	s_nop 0
	s_nop 0
	v_pk_mul_f32 v[146:147], v[146:147], v[166:167]
	s_nop 0
	v_pk_mul_f32 v[74:75], v[74:75], v[146:147]
	s_nop 0
	s_nop 0
	s_waitcnt vmcnt(0)
	v_lshlrev_b32_e32 v0, 16, v232
	v_mul_f32_e32 v0, 0xbfb8aa3b, v0
	v_exp_f32_e32 v0, v0
	s_nop 0
	v_min_f32_e32 v166, 0x7149f2ca, v0
	v_lshlrev_b32_e32 v0, 16, v230
	v_mul_f32_e32 v0, 0xbfb8aa3b, v0
	v_exp_f32_e32 v0, v0
	s_nop 0
	v_min_f32_e32 v0, 0x7149f2ca, v0
	v_add_f32_e32 v0, 1.0, v0
	v_rcp_f32_e32 v168, v0
	v_and_b32_e32 v0, 0xffff0000, v232
	v_mul_f32_e32 v0, 0xbfb8aa3b, v0
	v_exp_f32_e32 v0, v0
	s_nop 0
	v_min_f32_e32 v167, 0x7149f2ca, v0
	v_and_b32_e32 v0, 0xffff0000, v230
	v_mul_f32_e32 v0, 0xbfb8aa3b, v0
	v_exp_f32_e32 v0, v0
	v_pk_add_f32 v[166:167], v[166:167], 1.0 op_sel_hi:[1,0]
	v_min_f32_e32 v0, 0x7149f2ca, v0
	v_add_f32_e32 v0, 1.0, v0
	v_rcp_f32_e32 v169, v0
	v_lshlrev_b32_e32 v0, 16, v233
	v_mul_f32_e32 v0, 0xbfb8aa3b, v0
	v_exp_f32_e32 v0, v0
	v_pk_mul_f32 v[166:167], v[166:167], v[168:169]
	v_min_f32_e32 v2, 0x7149f2ca, v0
	v_lshlrev_b32_e32 v0, 16, v231
	v_mul_f32_e32 v0, 0xbfb8aa3b, v0
	v_exp_f32_e32 v0, v0
	v_pk_mul_f32 v[68:69], v[68:69], v[166:167]
	v_min_f32_e32 v0, 0x7149f2ca, v0
	v_add_f32_e32 v0, 1.0, v0
	v_rcp_f32_e32 v146, v0
	v_and_b32_e32 v0, 0xffff0000, v233
	v_mul_f32_e32 v0, 0xbfb8aa3b, v0
	v_exp_f32_e32 v0, v0
	s_nop 0
	v_min_f32_e32 v3, 0x7149f2ca, v0
	v_and_b32_e32 v0, 0xffff0000, v231
	v_mul_f32_e32 v0, 0xbfb8aa3b, v0
	v_exp_f32_e32 v0, v0
	v_pk_add_f32 v[2:3], v[2:3], 1.0 op_sel_hi:[1,0]
	v_min_f32_e32 v0, 0x7149f2ca, v0
	v_add_f32_e32 v0, 1.0, v0
	v_rcp_f32_e32 v147, v0
	v_mov_b32_e32 v0, v155
	v_pk_mul_f32 v[2:3], v[2:3], v[146:147]
	s_nop 0
	v_pk_mul_f32 v[70:71], v[70:71], v[2:3]
	s_nop 0
	s_nop 0
	v_mad_u64_u32 v[2:3], s[28:29], v0, s30, v[136:137]
	v_mov_b32_e32 v215, 0
	v_add_u32_e32 v214, s13, v2
	v_lshlrev_b64 v[216:217], 1, v[214:215]
	v_lshl_add_u64 v[218:219], s[4:5], 0, v[216:217]
	v_lshl_add_u64 v[220:221], s[8:9], 0, v[216:217]
	global_load_dwordx2 v[218:219], v[218:219], off
	global_load_dwordx2 v[220:221], v[220:221], off
	v_add_u32_e32 v214, s56, v2
	v_lshlrev_b64 v[216:217], 1, v[214:215]
	v_lshl_add_u64 v[222:223], s[4:5], 0, v[216:217]
	v_lshl_add_u64 v[224:225], s[8:9], 0, v[216:217]
	global_load_dwordx2 v[222:223], v[222:223], off
	global_load_dwordx2 v[224:225], v[224:225], off
	v_add_u32_e32 v214, s57, v2
	v_lshlrev_b64 v[216:217], 1, v[214:215]
	v_lshl_add_u64 v[226:227], s[4:5], 0, v[216:217]
	v_lshl_add_u64 v[228:229], s[8:9], 0, v[216:217]
	global_load_dwordx2 v[226:227], v[226:227], off
	global_load_dwordx2 v[228:229], v[228:229], off
	v_add_u32_e32 v214, s58, v2
	v_lshlrev_b64 v[216:217], 1, v[214:215]
	v_lshl_add_u64 v[230:231], s[4:5], 0, v[216:217]
	v_lshl_add_u64 v[232:233], s[8:9], 0, v[216:217]
	global_load_dwordx2 v[230:231], v[230:231], off
	global_load_dwordx2 v[232:233], v[232:233], off
	s_nop 0
	s_nop 0
	s_nop 0
	s_nop 0
	s_waitcnt vmcnt(6)
	v_lshlrev_b32_e32 v0, 16, v220
	v_mul_f32_e32 v0, 0xbfb8aa3b, v0
	v_exp_f32_e32 v0, v0
	s_nop 0
	v_min_f32_e32 v168, 0x7149f2ca, v0
	v_lshlrev_b32_e32 v0, 16, v218
	v_mul_f32_e32 v0, 0xbfb8aa3b, v0
	v_exp_f32_e32 v0, v0
	s_nop 0
	v_min_f32_e32 v0, 0x7149f2ca, v0
	v_add_f32_e32 v0, 1.0, v0
	v_rcp_f32_e32 v170, v0
	v_and_b32_e32 v0, 0xffff0000, v220
	v_mul_f32_e32 v0, 0xbfb8aa3b, v0
	v_exp_f32_e32 v0, v0
	s_nop 0
	v_min_f32_e32 v169, 0x7149f2ca, v0
	v_and_b32_e32 v0, 0xffff0000, v218
	v_mul_f32_e32 v0, 0xbfb8aa3b, v0
	v_exp_f32_e32 v0, v0
	v_pk_add_f32 v[168:169], v[168:169], 1.0 op_sel_hi:[1,0]
	v_min_f32_e32 v0, 0x7149f2ca, v0
	v_add_f32_e32 v0, 1.0, v0
	v_rcp_f32_e32 v171, v0
	v_lshlrev_b32_e32 v0, 16, v221
	v_mul_f32_e32 v0, 0xbfb8aa3b, v0
	v_exp_f32_e32 v0, v0
	v_pk_mul_f32 v[168:169], v[168:169], v[170:171]
	v_min_f32_e32 v146, 0x7149f2ca, v0
	v_lshlrev_b32_e32 v0, 16, v219
	v_mul_f32_e32 v0, 0xbfb8aa3b, v0
	v_exp_f32_e32 v0, v0
	v_pk_mul_f32 v[64:65], v[64:65], v[168:169]
	v_min_f32_e32 v0, 0x7149f2ca, v0
	v_add_f32_e32 v0, 1.0, v0
	v_rcp_f32_e32 v166, v0
	v_and_b32_e32 v0, 0xffff0000, v221
	v_mul_f32_e32 v0, 0xbfb8aa3b, v0
	v_exp_f32_e32 v0, v0
	s_nop 0
	v_min_f32_e32 v147, 0x7149f2ca, v0
	v_and_b32_e32 v0, 0xffff0000, v219
	v_mul_f32_e32 v0, 0xbfb8aa3b, v0
	v_exp_f32_e32 v0, v0
	v_pk_add_f32 v[146:147], v[146:147], 1.0 op_sel_hi:[1,0]
	v_min_f32_e32 v0, 0x7149f2ca, v0
	v_add_f32_e32 v0, 1.0, v0
	v_rcp_f32_e32 v167, v0
	s_nop 0
	v_pk_mul_f32 v[146:147], v[146:147], v[166:167]
	s_nop 0
	v_pk_mul_f32 v[66:67], v[66:67], v[146:147]
	s_nop 0
	s_nop 0
	s_nop 0
	s_waitcnt vmcnt(4)
	v_lshlrev_b32_e32 v0, 16, v224
	v_mul_f32_e32 v0, 0xbfb8aa3b, v0
	v_exp_f32_e32 v0, v0
	s_nop 0
	v_min_f32_e32 v168, 0x7149f2ca, v0
	v_lshlrev_b32_e32 v0, 16, v222
	v_mul_f32_e32 v0, 0xbfb8aa3b, v0
	v_exp_f32_e32 v0, v0
	s_nop 0
	v_min_f32_e32 v0, 0x7149f2ca, v0
	v_add_f32_e32 v0, 1.0, v0
	v_rcp_f32_e32 v170, v0
	v_and_b32_e32 v0, 0xffff0000, v224
	v_mul_f32_e32 v0, 0xbfb8aa3b, v0
	v_exp_f32_e32 v0, v0
	s_nop 0
	v_min_f32_e32 v169, 0x7149f2ca, v0
	v_and_b32_e32 v0, 0xffff0000, v222
	v_mul_f32_e32 v0, 0xbfb8aa3b, v0
	v_exp_f32_e32 v0, v0
	v_pk_add_f32 v[168:169], v[168:169], 1.0 op_sel_hi:[1,0]
	v_min_f32_e32 v0, 0x7149f2ca, v0
	v_add_f32_e32 v0, 1.0, v0
	v_rcp_f32_e32 v171, v0
	v_lshlrev_b32_e32 v0, 16, v225
	v_mul_f32_e32 v0, 0xbfb8aa3b, v0
	v_exp_f32_e32 v0, v0
	v_pk_mul_f32 v[168:169], v[168:169], v[170:171]
	v_min_f32_e32 v146, 0x7149f2ca, v0
	v_lshlrev_b32_e32 v0, 16, v223
	v_mul_f32_e32 v0, 0xbfb8aa3b, v0
	v_exp_f32_e32 v0, v0
	v_pk_mul_f32 v[60:61], v[60:61], v[168:169]
	v_min_f32_e32 v0, 0x7149f2ca, v0
	v_add_f32_e32 v0, 1.0, v0
	v_rcp_f32_e32 v166, v0
	v_and_b32_e32 v0, 0xffff0000, v225
	v_mul_f32_e32 v0, 0xbfb8aa3b, v0
	v_exp_f32_e32 v0, v0
	s_nop 0
	v_min_f32_e32 v147, 0x7149f2ca, v0
	v_and_b32_e32 v0, 0xffff0000, v223
	v_mul_f32_e32 v0, 0xbfb8aa3b, v0
	v_exp_f32_e32 v0, v0
	v_pk_add_f32 v[146:147], v[146:147], 1.0 op_sel_hi:[1,0]
	v_min_f32_e32 v0, 0x7149f2ca, v0
	v_add_f32_e32 v0, 1.0, v0
	v_rcp_f32_e32 v167, v0
	s_nop 0
	v_pk_mul_f32 v[146:147], v[146:147], v[166:167]
	s_nop 0
	v_pk_mul_f32 v[62:63], v[62:63], v[146:147]
	s_nop 0
	s_nop 0
	s_nop 0
	s_waitcnt vmcnt(2)
	v_lshlrev_b32_e32 v0, 16, v228
	v_mul_f32_e32 v0, 0xbfb8aa3b, v0
	v_exp_f32_e32 v0, v0
	s_nop 0
	v_min_f32_e32 v168, 0x7149f2ca, v0
	v_lshlrev_b32_e32 v0, 16, v226
	v_mul_f32_e32 v0, 0xbfb8aa3b, v0
	v_exp_f32_e32 v0, v0
	s_nop 0
	v_min_f32_e32 v0, 0x7149f2ca, v0
	v_add_f32_e32 v0, 1.0, v0
	v_rcp_f32_e32 v170, v0
	v_and_b32_e32 v0, 0xffff0000, v228
	v_mul_f32_e32 v0, 0xbfb8aa3b, v0
	v_exp_f32_e32 v0, v0
	s_nop 0
	v_min_f32_e32 v169, 0x7149f2ca, v0
	v_and_b32_e32 v0, 0xffff0000, v226
	v_mul_f32_e32 v0, 0xbfb8aa3b, v0
	v_exp_f32_e32 v0, v0
	v_pk_add_f32 v[168:169], v[168:169], 1.0 op_sel_hi:[1,0]
	v_min_f32_e32 v0, 0x7149f2ca, v0
	v_add_f32_e32 v0, 1.0, v0
	v_rcp_f32_e32 v171, v0
	v_lshlrev_b32_e32 v0, 16, v229
	v_mul_f32_e32 v0, 0xbfb8aa3b, v0
	v_exp_f32_e32 v0, v0
	v_pk_mul_f32 v[168:169], v[168:169], v[170:171]
	v_min_f32_e32 v146, 0x7149f2ca, v0
	v_lshlrev_b32_e32 v0, 16, v227
	v_mul_f32_e32 v0, 0xbfb8aa3b, v0
	v_exp_f32_e32 v0, v0
	v_pk_mul_f32 v[56:57], v[56:57], v[168:169]
	v_min_f32_e32 v0, 0x7149f2ca, v0
	v_add_f32_e32 v0, 1.0, v0
	v_rcp_f32_e32 v166, v0
	v_and_b32_e32 v0, 0xffff0000, v229
	v_mul_f32_e32 v0, 0xbfb8aa3b, v0
	v_exp_f32_e32 v0, v0
	s_nop 0
	v_min_f32_e32 v147, 0x7149f2ca, v0
	v_and_b32_e32 v0, 0xffff0000, v227
	v_mul_f32_e32 v0, 0xbfb8aa3b, v0
	v_exp_f32_e32 v0, v0
	v_pk_add_f32 v[146:147], v[146:147], 1.0 op_sel_hi:[1,0]
	v_min_f32_e32 v0, 0x7149f2ca, v0
	v_add_f32_e32 v0, 1.0, v0
	v_rcp_f32_e32 v167, v0
	s_nop 0
	s_nop 0
	v_pk_mul_f32 v[146:147], v[146:147], v[166:167]
	s_nop 0
	v_pk_mul_f32 v[58:59], v[58:59], v[146:147]
	s_nop 0
	s_nop 0
	s_waitcnt vmcnt(0)
	v_lshlrev_b32_e32 v0, 16, v232
	v_mul_f32_e32 v0, 0xbfb8aa3b, v0
	v_exp_f32_e32 v0, v0
	s_nop 0
	v_min_f32_e32 v166, 0x7149f2ca, v0
	v_lshlrev_b32_e32 v0, 16, v230
	v_mul_f32_e32 v0, 0xbfb8aa3b, v0
	v_exp_f32_e32 v0, v0
	s_nop 0
	v_min_f32_e32 v0, 0x7149f2ca, v0
	v_add_f32_e32 v0, 1.0, v0
	v_rcp_f32_e32 v168, v0
	v_and_b32_e32 v0, 0xffff0000, v232
	v_mul_f32_e32 v0, 0xbfb8aa3b, v0
	v_exp_f32_e32 v0, v0
	s_nop 0
	v_min_f32_e32 v167, 0x7149f2ca, v0
	v_and_b32_e32 v0, 0xffff0000, v230
	v_mul_f32_e32 v0, 0xbfb8aa3b, v0
	v_exp_f32_e32 v0, v0
	v_pk_add_f32 v[166:167], v[166:167], 1.0 op_sel_hi:[1,0]
	v_min_f32_e32 v0, 0x7149f2ca, v0
	v_add_f32_e32 v0, 1.0, v0
	v_rcp_f32_e32 v169, v0
	v_lshlrev_b32_e32 v0, 16, v233
	v_mul_f32_e32 v0, 0xbfb8aa3b, v0
	v_exp_f32_e32 v0, v0
	v_pk_mul_f32 v[166:167], v[166:167], v[168:169]
	v_min_f32_e32 v2, 0x7149f2ca, v0
	v_lshlrev_b32_e32 v0, 16, v231
	v_mul_f32_e32 v0, 0xbfb8aa3b, v0
	v_exp_f32_e32 v0, v0
	v_pk_mul_f32 v[52:53], v[52:53], v[166:167]
	v_min_f32_e32 v0, 0x7149f2ca, v0
	v_add_f32_e32 v0, 1.0, v0
	v_rcp_f32_e32 v146, v0
	v_and_b32_e32 v0, 0xffff0000, v233
	v_mul_f32_e32 v0, 0xbfb8aa3b, v0
	v_exp_f32_e32 v0, v0
	s_nop 0
	v_min_f32_e32 v3, 0x7149f2ca, v0
	v_and_b32_e32 v0, 0xffff0000, v231
	v_mul_f32_e32 v0, 0xbfb8aa3b, v0
	v_exp_f32_e32 v0, v0
	v_pk_add_f32 v[2:3], v[2:3], 1.0 op_sel_hi:[1,0]
	v_min_f32_e32 v0, 0x7149f2ca, v0
	v_add_f32_e32 v0, 1.0, v0
	v_rcp_f32_e32 v147, v0
	v_mov_b32_e32 v0, v156
	v_pk_mul_f32 v[2:3], v[2:3], v[146:147]
	s_nop 0
	v_pk_mul_f32 v[54:55], v[54:55], v[2:3]
	s_nop 0
	s_nop 0
	v_mad_u64_u32 v[2:3], s[28:29], v0, s30, v[136:137]
	v_mov_b32_e32 v215, 0
	v_add_u32_e32 v214, s13, v2
	v_lshlrev_b64 v[216:217], 1, v[214:215]
	v_lshl_add_u64 v[218:219], s[4:5], 0, v[216:217]
	v_lshl_add_u64 v[220:221], s[8:9], 0, v[216:217]
	global_load_dwordx2 v[218:219], v[218:219], off
	global_load_dwordx2 v[220:221], v[220:221], off
	v_add_u32_e32 v214, s56, v2
	v_lshlrev_b64 v[216:217], 1, v[214:215]
	v_lshl_add_u64 v[222:223], s[4:5], 0, v[216:217]
	v_lshl_add_u64 v[224:225], s[8:9], 0, v[216:217]
	global_load_dwordx2 v[222:223], v[222:223], off
	global_load_dwordx2 v[224:225], v[224:225], off
	v_add_u32_e32 v214, s57, v2
	v_lshlrev_b64 v[216:217], 1, v[214:215]
	v_lshl_add_u64 v[226:227], s[4:5], 0, v[216:217]
	v_lshl_add_u64 v[228:229], s[8:9], 0, v[216:217]
	global_load_dwordx2 v[226:227], v[226:227], off
	global_load_dwordx2 v[228:229], v[228:229], off
	v_add_u32_e32 v214, s58, v2
	v_lshlrev_b64 v[216:217], 1, v[214:215]
	v_lshl_add_u64 v[230:231], s[4:5], 0, v[216:217]
	v_lshl_add_u64 v[232:233], s[8:9], 0, v[216:217]
	global_load_dwordx2 v[230:231], v[230:231], off
	global_load_dwordx2 v[232:233], v[232:233], off
	s_nop 0
	s_nop 0
	s_nop 0
	s_nop 0
	s_waitcnt vmcnt(6)
	v_lshlrev_b32_e32 v0, 16, v220
	v_mul_f32_e32 v0, 0xbfb8aa3b, v0
	v_exp_f32_e32 v0, v0
	s_nop 0
	v_min_f32_e32 v168, 0x7149f2ca, v0
	v_lshlrev_b32_e32 v0, 16, v218
	v_mul_f32_e32 v0, 0xbfb8aa3b, v0
	v_exp_f32_e32 v0, v0
	s_nop 0
	v_min_f32_e32 v0, 0x7149f2ca, v0
	v_add_f32_e32 v0, 1.0, v0
	v_rcp_f32_e32 v170, v0
	v_and_b32_e32 v0, 0xffff0000, v220
	v_mul_f32_e32 v0, 0xbfb8aa3b, v0
	v_exp_f32_e32 v0, v0
	s_nop 0
	v_min_f32_e32 v169, 0x7149f2ca, v0
	v_and_b32_e32 v0, 0xffff0000, v218
	v_mul_f32_e32 v0, 0xbfb8aa3b, v0
	v_exp_f32_e32 v0, v0
	v_pk_add_f32 v[168:169], v[168:169], 1.0 op_sel_hi:[1,0]
	v_min_f32_e32 v0, 0x7149f2ca, v0
	v_add_f32_e32 v0, 1.0, v0
	v_rcp_f32_e32 v171, v0
	v_lshlrev_b32_e32 v0, 16, v221
	v_mul_f32_e32 v0, 0xbfb8aa3b, v0
	v_exp_f32_e32 v0, v0
	v_pk_mul_f32 v[168:169], v[168:169], v[170:171]
	v_min_f32_e32 v146, 0x7149f2ca, v0
	v_lshlrev_b32_e32 v0, 16, v219
	v_mul_f32_e32 v0, 0xbfb8aa3b, v0
	v_exp_f32_e32 v0, v0
	v_pk_mul_f32 v[48:49], v[48:49], v[168:169]
	v_min_f32_e32 v0, 0x7149f2ca, v0
	v_add_f32_e32 v0, 1.0, v0
	v_rcp_f32_e32 v166, v0
	v_and_b32_e32 v0, 0xffff0000, v221
	v_mul_f32_e32 v0, 0xbfb8aa3b, v0
	v_exp_f32_e32 v0, v0
	s_nop 0
	v_min_f32_e32 v147, 0x7149f2ca, v0
	v_and_b32_e32 v0, 0xffff0000, v219
	v_mul_f32_e32 v0, 0xbfb8aa3b, v0
	v_exp_f32_e32 v0, v0
	v_pk_add_f32 v[146:147], v[146:147], 1.0 op_sel_hi:[1,0]
	v_min_f32_e32 v0, 0x7149f2ca, v0
	v_add_f32_e32 v0, 1.0, v0
	v_rcp_f32_e32 v167, v0
	s_nop 0
	v_pk_mul_f32 v[146:147], v[146:147], v[166:167]
	s_nop 0
	v_pk_mul_f32 v[50:51], v[50:51], v[146:147]
	s_nop 0
	s_nop 0
	s_nop 0
	s_waitcnt vmcnt(4)
	v_lshlrev_b32_e32 v0, 16, v224
	v_mul_f32_e32 v0, 0xbfb8aa3b, v0
	v_exp_f32_e32 v0, v0
	s_nop 0
	v_min_f32_e32 v168, 0x7149f2ca, v0
	v_lshlrev_b32_e32 v0, 16, v222
	v_mul_f32_e32 v0, 0xbfb8aa3b, v0
	v_exp_f32_e32 v0, v0
	s_nop 0
	v_min_f32_e32 v0, 0x7149f2ca, v0
	v_add_f32_e32 v0, 1.0, v0
	v_rcp_f32_e32 v170, v0
	v_and_b32_e32 v0, 0xffff0000, v224
	v_mul_f32_e32 v0, 0xbfb8aa3b, v0
	v_exp_f32_e32 v0, v0
	s_nop 0
	v_min_f32_e32 v169, 0x7149f2ca, v0
	v_and_b32_e32 v0, 0xffff0000, v222
	v_mul_f32_e32 v0, 0xbfb8aa3b, v0
	v_exp_f32_e32 v0, v0
	v_pk_add_f32 v[168:169], v[168:169], 1.0 op_sel_hi:[1,0]
	v_min_f32_e32 v0, 0x7149f2ca, v0
	v_add_f32_e32 v0, 1.0, v0
	v_rcp_f32_e32 v171, v0
	v_lshlrev_b32_e32 v0, 16, v225
	v_mul_f32_e32 v0, 0xbfb8aa3b, v0
	v_exp_f32_e32 v0, v0
	v_pk_mul_f32 v[168:169], v[168:169], v[170:171]
	v_min_f32_e32 v146, 0x7149f2ca, v0
	v_lshlrev_b32_e32 v0, 16, v223
	v_mul_f32_e32 v0, 0xbfb8aa3b, v0
	v_exp_f32_e32 v0, v0
	v_pk_mul_f32 v[44:45], v[44:45], v[168:169]
	v_min_f32_e32 v0, 0x7149f2ca, v0
	v_add_f32_e32 v0, 1.0, v0
	v_rcp_f32_e32 v166, v0
	v_and_b32_e32 v0, 0xffff0000, v225
	v_mul_f32_e32 v0, 0xbfb8aa3b, v0
	v_exp_f32_e32 v0, v0
	s_nop 0
	v_min_f32_e32 v147, 0x7149f2ca, v0
	v_and_b32_e32 v0, 0xffff0000, v223
	v_mul_f32_e32 v0, 0xbfb8aa3b, v0
	v_exp_f32_e32 v0, v0
	v_pk_add_f32 v[146:147], v[146:147], 1.0 op_sel_hi:[1,0]
	v_min_f32_e32 v0, 0x7149f2ca, v0
	v_add_f32_e32 v0, 1.0, v0
	v_rcp_f32_e32 v167, v0
	s_nop 0
	v_pk_mul_f32 v[146:147], v[146:147], v[166:167]
	s_nop 0
	v_pk_mul_f32 v[46:47], v[46:47], v[146:147]
	s_nop 0
	s_nop 0
	s_nop 0
	s_waitcnt vmcnt(2)
	v_lshlrev_b32_e32 v0, 16, v228
	v_mul_f32_e32 v0, 0xbfb8aa3b, v0
	v_exp_f32_e32 v0, v0
	s_nop 0
	v_min_f32_e32 v168, 0x7149f2ca, v0
	v_lshlrev_b32_e32 v0, 16, v226
	v_mul_f32_e32 v0, 0xbfb8aa3b, v0
	v_exp_f32_e32 v0, v0
	s_nop 0
	v_min_f32_e32 v0, 0x7149f2ca, v0
	v_add_f32_e32 v0, 1.0, v0
	v_rcp_f32_e32 v170, v0
	v_and_b32_e32 v0, 0xffff0000, v228
	v_mul_f32_e32 v0, 0xbfb8aa3b, v0
	v_exp_f32_e32 v0, v0
	s_nop 0
	v_min_f32_e32 v169, 0x7149f2ca, v0
	v_and_b32_e32 v0, 0xffff0000, v226
	v_mul_f32_e32 v0, 0xbfb8aa3b, v0
	v_exp_f32_e32 v0, v0
	v_pk_add_f32 v[168:169], v[168:169], 1.0 op_sel_hi:[1,0]
	v_min_f32_e32 v0, 0x7149f2ca, v0
	v_add_f32_e32 v0, 1.0, v0
	v_rcp_f32_e32 v171, v0
	v_lshlrev_b32_e32 v0, 16, v229
	v_mul_f32_e32 v0, 0xbfb8aa3b, v0
	v_exp_f32_e32 v0, v0
	v_pk_mul_f32 v[168:169], v[168:169], v[170:171]
	v_min_f32_e32 v146, 0x7149f2ca, v0
	v_lshlrev_b32_e32 v0, 16, v227
	v_mul_f32_e32 v0, 0xbfb8aa3b, v0
	v_exp_f32_e32 v0, v0
	v_pk_mul_f32 v[40:41], v[40:41], v[168:169]
	v_min_f32_e32 v0, 0x7149f2ca, v0
	v_add_f32_e32 v0, 1.0, v0
	v_rcp_f32_e32 v166, v0
	v_and_b32_e32 v0, 0xffff0000, v229
	v_mul_f32_e32 v0, 0xbfb8aa3b, v0
	v_exp_f32_e32 v0, v0
	s_nop 0
	v_min_f32_e32 v147, 0x7149f2ca, v0
	v_and_b32_e32 v0, 0xffff0000, v227
	v_mul_f32_e32 v0, 0xbfb8aa3b, v0
	v_exp_f32_e32 v0, v0
	v_pk_add_f32 v[146:147], v[146:147], 1.0 op_sel_hi:[1,0]
	v_min_f32_e32 v0, 0x7149f2ca, v0
	v_add_f32_e32 v0, 1.0, v0
	v_rcp_f32_e32 v167, v0
	s_nop 0
	s_nop 0
	v_pk_mul_f32 v[146:147], v[146:147], v[166:167]
	s_nop 0
	v_pk_mul_f32 v[42:43], v[42:43], v[146:147]
	s_nop 0
	s_nop 0
	s_waitcnt vmcnt(0)
	v_lshlrev_b32_e32 v0, 16, v232
	v_mul_f32_e32 v0, 0xbfb8aa3b, v0
	v_exp_f32_e32 v0, v0
	s_nop 0
	v_min_f32_e32 v166, 0x7149f2ca, v0
	v_lshlrev_b32_e32 v0, 16, v230
	v_mul_f32_e32 v0, 0xbfb8aa3b, v0
	v_exp_f32_e32 v0, v0
	s_nop 0
	v_min_f32_e32 v0, 0x7149f2ca, v0
	v_add_f32_e32 v0, 1.0, v0
	v_rcp_f32_e32 v168, v0
	v_and_b32_e32 v0, 0xffff0000, v232
	v_mul_f32_e32 v0, 0xbfb8aa3b, v0
	v_exp_f32_e32 v0, v0
	s_nop 0
	v_min_f32_e32 v167, 0x7149f2ca, v0
	v_and_b32_e32 v0, 0xffff0000, v230
	v_mul_f32_e32 v0, 0xbfb8aa3b, v0
	v_exp_f32_e32 v0, v0
	v_pk_add_f32 v[166:167], v[166:167], 1.0 op_sel_hi:[1,0]
	v_min_f32_e32 v0, 0x7149f2ca, v0
	v_add_f32_e32 v0, 1.0, v0
	v_rcp_f32_e32 v169, v0
	v_lshlrev_b32_e32 v0, 16, v233
	v_mul_f32_e32 v0, 0xbfb8aa3b, v0
	v_exp_f32_e32 v0, v0
	v_pk_mul_f32 v[166:167], v[166:167], v[168:169]
	v_min_f32_e32 v2, 0x7149f2ca, v0
	v_lshlrev_b32_e32 v0, 16, v231
	v_mul_f32_e32 v0, 0xbfb8aa3b, v0
	v_exp_f32_e32 v0, v0
	v_pk_mul_f32 v[36:37], v[36:37], v[166:167]
	v_min_f32_e32 v0, 0x7149f2ca, v0
	v_add_f32_e32 v0, 1.0, v0
	v_rcp_f32_e32 v146, v0
	v_and_b32_e32 v0, 0xffff0000, v233
	v_mul_f32_e32 v0, 0xbfb8aa3b, v0
	v_exp_f32_e32 v0, v0
	s_nop 0
	v_min_f32_e32 v3, 0x7149f2ca, v0
	v_and_b32_e32 v0, 0xffff0000, v231
	v_mul_f32_e32 v0, 0xbfb8aa3b, v0
	v_exp_f32_e32 v0, v0
	v_pk_add_f32 v[2:3], v[2:3], 1.0 op_sel_hi:[1,0]
	v_min_f32_e32 v0, 0x7149f2ca, v0
	v_add_f32_e32 v0, 1.0, v0
	v_rcp_f32_e32 v147, v0
	v_mov_b32_e32 v0, v157
	v_pk_mul_f32 v[2:3], v[2:3], v[146:147]
	s_nop 0
	v_pk_mul_f32 v[38:39], v[38:39], v[2:3]
	s_nop 0
	s_nop 0
	v_mad_u64_u32 v[2:3], s[28:29], v0, s30, v[136:137]
	v_mov_b32_e32 v215, 0
	v_add_u32_e32 v214, s13, v2
	v_lshlrev_b64 v[216:217], 1, v[214:215]
	v_lshl_add_u64 v[218:219], s[4:5], 0, v[216:217]
	v_lshl_add_u64 v[220:221], s[8:9], 0, v[216:217]
	global_load_dwordx2 v[218:219], v[218:219], off
	global_load_dwordx2 v[220:221], v[220:221], off
	v_add_u32_e32 v214, s56, v2
	v_lshlrev_b64 v[216:217], 1, v[214:215]
	v_lshl_add_u64 v[222:223], s[4:5], 0, v[216:217]
	v_lshl_add_u64 v[224:225], s[8:9], 0, v[216:217]
	global_load_dwordx2 v[222:223], v[222:223], off
	global_load_dwordx2 v[224:225], v[224:225], off
	v_add_u32_e32 v214, s57, v2
	v_lshlrev_b64 v[216:217], 1, v[214:215]
	v_lshl_add_u64 v[226:227], s[4:5], 0, v[216:217]
	v_lshl_add_u64 v[228:229], s[8:9], 0, v[216:217]
	global_load_dwordx2 v[226:227], v[226:227], off
	global_load_dwordx2 v[228:229], v[228:229], off
	v_add_u32_e32 v214, s58, v2
	v_lshlrev_b64 v[216:217], 1, v[214:215]
	v_lshl_add_u64 v[230:231], s[4:5], 0, v[216:217]
	v_lshl_add_u64 v[232:233], s[8:9], 0, v[216:217]
	global_load_dwordx2 v[230:231], v[230:231], off
	global_load_dwordx2 v[232:233], v[232:233], off
	s_nop 0
	s_nop 0
	s_nop 0
	s_nop 0
	s_waitcnt vmcnt(6)
	v_lshlrev_b32_e32 v0, 16, v220
	v_mul_f32_e32 v0, 0xbfb8aa3b, v0
	v_exp_f32_e32 v0, v0
	s_nop 0
	v_min_f32_e32 v168, 0x7149f2ca, v0
	v_lshlrev_b32_e32 v0, 16, v218
	v_mul_f32_e32 v0, 0xbfb8aa3b, v0
	v_exp_f32_e32 v0, v0
	s_nop 0
	v_min_f32_e32 v0, 0x7149f2ca, v0
	v_add_f32_e32 v0, 1.0, v0
	v_rcp_f32_e32 v170, v0
	v_and_b32_e32 v0, 0xffff0000, v220
	v_mul_f32_e32 v0, 0xbfb8aa3b, v0
	v_exp_f32_e32 v0, v0
	s_nop 0
	v_min_f32_e32 v169, 0x7149f2ca, v0
	v_and_b32_e32 v0, 0xffff0000, v218
	v_mul_f32_e32 v0, 0xbfb8aa3b, v0
	v_exp_f32_e32 v0, v0
	v_pk_add_f32 v[168:169], v[168:169], 1.0 op_sel_hi:[1,0]
	v_min_f32_e32 v0, 0x7149f2ca, v0
	v_add_f32_e32 v0, 1.0, v0
	v_rcp_f32_e32 v171, v0
	v_lshlrev_b32_e32 v0, 16, v221
	v_mul_f32_e32 v0, 0xbfb8aa3b, v0
	v_exp_f32_e32 v0, v0
	v_pk_mul_f32 v[168:169], v[168:169], v[170:171]
	v_min_f32_e32 v146, 0x7149f2ca, v0
	v_lshlrev_b32_e32 v0, 16, v219
	v_mul_f32_e32 v0, 0xbfb8aa3b, v0
	v_exp_f32_e32 v0, v0
	v_pk_mul_f32 v[32:33], v[32:33], v[168:169]
	v_min_f32_e32 v0, 0x7149f2ca, v0
	v_add_f32_e32 v0, 1.0, v0
	v_rcp_f32_e32 v166, v0
	v_and_b32_e32 v0, 0xffff0000, v221
	v_mul_f32_e32 v0, 0xbfb8aa3b, v0
	v_exp_f32_e32 v0, v0
	s_nop 0
	v_min_f32_e32 v147, 0x7149f2ca, v0
	v_and_b32_e32 v0, 0xffff0000, v219
	v_mul_f32_e32 v0, 0xbfb8aa3b, v0
	v_exp_f32_e32 v0, v0
	v_pk_add_f32 v[146:147], v[146:147], 1.0 op_sel_hi:[1,0]
	v_min_f32_e32 v0, 0x7149f2ca, v0
	v_add_f32_e32 v0, 1.0, v0
	v_rcp_f32_e32 v167, v0
	s_nop 0
	v_pk_mul_f32 v[146:147], v[146:147], v[166:167]
	s_nop 0
	v_pk_mul_f32 v[34:35], v[34:35], v[146:147]
	s_nop 0
	s_nop 0
	s_nop 0
	s_waitcnt vmcnt(4)
	v_lshlrev_b32_e32 v0, 16, v224
	v_mul_f32_e32 v0, 0xbfb8aa3b, v0
	v_exp_f32_e32 v0, v0
	s_nop 0
	v_min_f32_e32 v168, 0x7149f2ca, v0
	v_lshlrev_b32_e32 v0, 16, v222
	v_mul_f32_e32 v0, 0xbfb8aa3b, v0
	v_exp_f32_e32 v0, v0
	s_nop 0
	v_min_f32_e32 v0, 0x7149f2ca, v0
	v_add_f32_e32 v0, 1.0, v0
	v_rcp_f32_e32 v170, v0
	v_and_b32_e32 v0, 0xffff0000, v224
	v_mul_f32_e32 v0, 0xbfb8aa3b, v0
	v_exp_f32_e32 v0, v0
	s_nop 0
	v_min_f32_e32 v169, 0x7149f2ca, v0
	v_and_b32_e32 v0, 0xffff0000, v222
	v_mul_f32_e32 v0, 0xbfb8aa3b, v0
	v_exp_f32_e32 v0, v0
	v_pk_add_f32 v[168:169], v[168:169], 1.0 op_sel_hi:[1,0]
	v_min_f32_e32 v0, 0x7149f2ca, v0
	v_add_f32_e32 v0, 1.0, v0
	v_rcp_f32_e32 v171, v0
	v_lshlrev_b32_e32 v0, 16, v225
	v_mul_f32_e32 v0, 0xbfb8aa3b, v0
	v_exp_f32_e32 v0, v0
	v_pk_mul_f32 v[168:169], v[168:169], v[170:171]
	v_min_f32_e32 v146, 0x7149f2ca, v0
	v_lshlrev_b32_e32 v0, 16, v223
	v_mul_f32_e32 v0, 0xbfb8aa3b, v0
	v_exp_f32_e32 v0, v0
	v_pk_mul_f32 v[28:29], v[28:29], v[168:169]
	v_min_f32_e32 v0, 0x7149f2ca, v0
	v_add_f32_e32 v0, 1.0, v0
	v_rcp_f32_e32 v166, v0
	v_and_b32_e32 v0, 0xffff0000, v225
	v_mul_f32_e32 v0, 0xbfb8aa3b, v0
	v_exp_f32_e32 v0, v0
	s_nop 0
	v_min_f32_e32 v147, 0x7149f2ca, v0
	v_and_b32_e32 v0, 0xffff0000, v223
	v_mul_f32_e32 v0, 0xbfb8aa3b, v0
	v_exp_f32_e32 v0, v0
	v_pk_add_f32 v[146:147], v[146:147], 1.0 op_sel_hi:[1,0]
	v_min_f32_e32 v0, 0x7149f2ca, v0
	v_add_f32_e32 v0, 1.0, v0
	v_rcp_f32_e32 v167, v0
	s_nop 0
	v_pk_mul_f32 v[146:147], v[146:147], v[166:167]
	s_nop 0
	v_pk_mul_f32 v[30:31], v[30:31], v[146:147]
	s_nop 0
	s_nop 0
	s_nop 0
	s_waitcnt vmcnt(2)
	v_lshlrev_b32_e32 v0, 16, v228
	v_mul_f32_e32 v0, 0xbfb8aa3b, v0
	v_exp_f32_e32 v0, v0
	s_nop 0
	v_min_f32_e32 v168, 0x7149f2ca, v0
	v_lshlrev_b32_e32 v0, 16, v226
	v_mul_f32_e32 v0, 0xbfb8aa3b, v0
	v_exp_f32_e32 v0, v0
	s_nop 0
	v_min_f32_e32 v0, 0x7149f2ca, v0
	v_add_f32_e32 v0, 1.0, v0
	v_rcp_f32_e32 v170, v0
	v_and_b32_e32 v0, 0xffff0000, v228
	v_mul_f32_e32 v0, 0xbfb8aa3b, v0
	v_exp_f32_e32 v0, v0
	s_nop 0
	v_min_f32_e32 v169, 0x7149f2ca, v0
	v_and_b32_e32 v0, 0xffff0000, v226
	v_mul_f32_e32 v0, 0xbfb8aa3b, v0
	v_exp_f32_e32 v0, v0
	v_pk_add_f32 v[168:169], v[168:169], 1.0 op_sel_hi:[1,0]
	v_min_f32_e32 v0, 0x7149f2ca, v0
	v_add_f32_e32 v0, 1.0, v0
	v_rcp_f32_e32 v171, v0
	v_lshlrev_b32_e32 v0, 16, v229
	v_mul_f32_e32 v0, 0xbfb8aa3b, v0
	v_exp_f32_e32 v0, v0
	v_pk_mul_f32 v[168:169], v[168:169], v[170:171]
	v_min_f32_e32 v146, 0x7149f2ca, v0
	v_lshlrev_b32_e32 v0, 16, v227
	v_mul_f32_e32 v0, 0xbfb8aa3b, v0
	v_exp_f32_e32 v0, v0
	v_pk_mul_f32 v[24:25], v[24:25], v[168:169]
	v_min_f32_e32 v0, 0x7149f2ca, v0
	v_add_f32_e32 v0, 1.0, v0
	v_rcp_f32_e32 v166, v0
	v_and_b32_e32 v0, 0xffff0000, v229
	v_mul_f32_e32 v0, 0xbfb8aa3b, v0
	v_exp_f32_e32 v0, v0
	s_nop 0
	v_min_f32_e32 v147, 0x7149f2ca, v0
	v_and_b32_e32 v0, 0xffff0000, v227
	v_mul_f32_e32 v0, 0xbfb8aa3b, v0
	v_exp_f32_e32 v0, v0
	v_pk_add_f32 v[146:147], v[146:147], 1.0 op_sel_hi:[1,0]
	v_min_f32_e32 v0, 0x7149f2ca, v0
	v_add_f32_e32 v0, 1.0, v0
	v_rcp_f32_e32 v167, v0
	s_nop 0
	s_nop 0
	v_pk_mul_f32 v[146:147], v[146:147], v[166:167]
	s_nop 0
	v_pk_mul_f32 v[26:27], v[26:27], v[146:147]
	s_nop 0
	s_nop 0
	s_waitcnt vmcnt(0)
	v_lshlrev_b32_e32 v0, 16, v232
	v_mul_f32_e32 v0, 0xbfb8aa3b, v0
	v_exp_f32_e32 v0, v0
	s_nop 0
	v_min_f32_e32 v166, 0x7149f2ca, v0
	v_lshlrev_b32_e32 v0, 16, v230
	v_mul_f32_e32 v0, 0xbfb8aa3b, v0
	v_exp_f32_e32 v0, v0
	s_nop 0
	v_min_f32_e32 v0, 0x7149f2ca, v0
	v_add_f32_e32 v0, 1.0, v0
	v_rcp_f32_e32 v168, v0
	v_and_b32_e32 v0, 0xffff0000, v232
	v_mul_f32_e32 v0, 0xbfb8aa3b, v0
	v_exp_f32_e32 v0, v0
	s_nop 0
	v_min_f32_e32 v167, 0x7149f2ca, v0
	v_and_b32_e32 v0, 0xffff0000, v230
	v_mul_f32_e32 v0, 0xbfb8aa3b, v0
	v_exp_f32_e32 v0, v0
	v_pk_add_f32 v[166:167], v[166:167], 1.0 op_sel_hi:[1,0]
	v_min_f32_e32 v0, 0x7149f2ca, v0
	v_add_f32_e32 v0, 1.0, v0
	v_rcp_f32_e32 v169, v0
	v_lshlrev_b32_e32 v0, 16, v233
	v_mul_f32_e32 v0, 0xbfb8aa3b, v0
	v_exp_f32_e32 v0, v0
	v_pk_mul_f32 v[166:167], v[166:167], v[168:169]
	v_min_f32_e32 v2, 0x7149f2ca, v0
	v_lshlrev_b32_e32 v0, 16, v231
	v_mul_f32_e32 v0, 0xbfb8aa3b, v0
	v_exp_f32_e32 v0, v0
	v_pk_mul_f32 v[20:21], v[20:21], v[166:167]
	v_min_f32_e32 v0, 0x7149f2ca, v0
	v_add_f32_e32 v0, 1.0, v0
	v_rcp_f32_e32 v146, v0
	v_and_b32_e32 v0, 0xffff0000, v233
	v_mul_f32_e32 v0, 0xbfb8aa3b, v0
	v_exp_f32_e32 v0, v0
	s_nop 0
	v_min_f32_e32 v3, 0x7149f2ca, v0
	v_and_b32_e32 v0, 0xffff0000, v231
	v_mul_f32_e32 v0, 0xbfb8aa3b, v0
	v_exp_f32_e32 v0, v0
	v_pk_add_f32 v[2:3], v[2:3], 1.0 op_sel_hi:[1,0]
	v_min_f32_e32 v0, 0x7149f2ca, v0
	v_add_f32_e32 v0, 1.0, v0
	v_rcp_f32_e32 v147, v0
	v_mov_b32_e32 v0, v158
	v_pk_mul_f32 v[2:3], v[2:3], v[146:147]
	s_nop 0
	v_pk_mul_f32 v[22:23], v[22:23], v[2:3]
	s_nop 0
	s_nop 0
	v_mad_u64_u32 v[2:3], s[28:29], v0, s30, v[136:137]
	v_mov_b32_e32 v215, 0
	v_add_u32_e32 v214, s13, v2
	v_lshlrev_b64 v[216:217], 1, v[214:215]
	v_lshl_add_u64 v[218:219], s[4:5], 0, v[216:217]
	v_lshl_add_u64 v[220:221], s[8:9], 0, v[216:217]
	global_load_dwordx2 v[218:219], v[218:219], off
	global_load_dwordx2 v[220:221], v[220:221], off
	v_add_u32_e32 v214, s56, v2
	v_lshlrev_b64 v[216:217], 1, v[214:215]
	v_lshl_add_u64 v[222:223], s[4:5], 0, v[216:217]
	v_lshl_add_u64 v[224:225], s[8:9], 0, v[216:217]
	global_load_dwordx2 v[222:223], v[222:223], off
	global_load_dwordx2 v[224:225], v[224:225], off
	v_add_u32_e32 v214, s57, v2
	v_lshlrev_b64 v[216:217], 1, v[214:215]
	v_lshl_add_u64 v[226:227], s[4:5], 0, v[216:217]
	v_lshl_add_u64 v[228:229], s[8:9], 0, v[216:217]
	global_load_dwordx2 v[226:227], v[226:227], off
	global_load_dwordx2 v[228:229], v[228:229], off
	v_add_u32_e32 v214, s58, v2
	v_lshlrev_b64 v[216:217], 1, v[214:215]
	v_lshl_add_u64 v[230:231], s[4:5], 0, v[216:217]
	v_lshl_add_u64 v[232:233], s[8:9], 0, v[216:217]
	global_load_dwordx2 v[230:231], v[230:231], off
	global_load_dwordx2 v[232:233], v[232:233], off
	s_nop 0
	s_nop 0
	s_nop 0
	s_nop 0
	s_waitcnt vmcnt(6)
	v_lshlrev_b32_e32 v0, 16, v220
	v_mul_f32_e32 v0, 0xbfb8aa3b, v0
	v_exp_f32_e32 v0, v0
	s_nop 0
	v_min_f32_e32 v168, 0x7149f2ca, v0
	v_lshlrev_b32_e32 v0, 16, v218
	v_mul_f32_e32 v0, 0xbfb8aa3b, v0
	v_exp_f32_e32 v0, v0
	s_nop 0
	v_min_f32_e32 v0, 0x7149f2ca, v0
	v_add_f32_e32 v0, 1.0, v0
	v_rcp_f32_e32 v170, v0
	v_and_b32_e32 v0, 0xffff0000, v220
	v_mul_f32_e32 v0, 0xbfb8aa3b, v0
	v_exp_f32_e32 v0, v0
	s_nop 0
	v_min_f32_e32 v169, 0x7149f2ca, v0
	v_and_b32_e32 v0, 0xffff0000, v218
	v_mul_f32_e32 v0, 0xbfb8aa3b, v0
	v_exp_f32_e32 v0, v0
	v_pk_add_f32 v[168:169], v[168:169], 1.0 op_sel_hi:[1,0]
	v_min_f32_e32 v0, 0x7149f2ca, v0
	v_add_f32_e32 v0, 1.0, v0
	v_rcp_f32_e32 v171, v0
	v_lshlrev_b32_e32 v0, 16, v221
	v_mul_f32_e32 v0, 0xbfb8aa3b, v0
	v_exp_f32_e32 v0, v0
	v_pk_mul_f32 v[168:169], v[168:169], v[170:171]
	v_min_f32_e32 v146, 0x7149f2ca, v0
	v_lshlrev_b32_e32 v0, 16, v219
	v_mul_f32_e32 v0, 0xbfb8aa3b, v0
	v_exp_f32_e32 v0, v0
	v_pk_mul_f32 v[16:17], v[16:17], v[168:169]
	v_min_f32_e32 v0, 0x7149f2ca, v0
	v_add_f32_e32 v0, 1.0, v0
	v_rcp_f32_e32 v166, v0
	v_and_b32_e32 v0, 0xffff0000, v221
	v_mul_f32_e32 v0, 0xbfb8aa3b, v0
	v_exp_f32_e32 v0, v0
	s_nop 0
	v_min_f32_e32 v147, 0x7149f2ca, v0
	v_and_b32_e32 v0, 0xffff0000, v219
	v_mul_f32_e32 v0, 0xbfb8aa3b, v0
	v_exp_f32_e32 v0, v0
	v_pk_add_f32 v[146:147], v[146:147], 1.0 op_sel_hi:[1,0]
	v_min_f32_e32 v0, 0x7149f2ca, v0
	v_add_f32_e32 v0, 1.0, v0
	v_rcp_f32_e32 v167, v0
	s_nop 0
	v_pk_mul_f32 v[146:147], v[146:147], v[166:167]
	s_nop 0
	v_pk_mul_f32 v[18:19], v[18:19], v[146:147]
	s_nop 0
	s_nop 0
	s_nop 0
	s_waitcnt vmcnt(4)
	v_lshlrev_b32_e32 v0, 16, v224
	v_mul_f32_e32 v0, 0xbfb8aa3b, v0
	v_exp_f32_e32 v0, v0
	s_nop 0
	v_min_f32_e32 v168, 0x7149f2ca, v0
	v_lshlrev_b32_e32 v0, 16, v222
	v_mul_f32_e32 v0, 0xbfb8aa3b, v0
	v_exp_f32_e32 v0, v0
	s_nop 0
	v_min_f32_e32 v0, 0x7149f2ca, v0
	v_add_f32_e32 v0, 1.0, v0
	v_rcp_f32_e32 v170, v0
	v_and_b32_e32 v0, 0xffff0000, v224
	v_mul_f32_e32 v0, 0xbfb8aa3b, v0
	v_exp_f32_e32 v0, v0
	s_nop 0
	v_min_f32_e32 v169, 0x7149f2ca, v0
	v_and_b32_e32 v0, 0xffff0000, v222
	v_mul_f32_e32 v0, 0xbfb8aa3b, v0
	v_exp_f32_e32 v0, v0
	v_pk_add_f32 v[168:169], v[168:169], 1.0 op_sel_hi:[1,0]
	v_min_f32_e32 v0, 0x7149f2ca, v0
	v_add_f32_e32 v0, 1.0, v0
	v_rcp_f32_e32 v171, v0
	v_lshlrev_b32_e32 v0, 16, v225
	v_mul_f32_e32 v0, 0xbfb8aa3b, v0
	v_exp_f32_e32 v0, v0
	v_pk_mul_f32 v[168:169], v[168:169], v[170:171]
	v_min_f32_e32 v146, 0x7149f2ca, v0
	v_lshlrev_b32_e32 v0, 16, v223
	v_mul_f32_e32 v0, 0xbfb8aa3b, v0
	v_exp_f32_e32 v0, v0
	v_pk_mul_f32 v[12:13], v[12:13], v[168:169]
	v_min_f32_e32 v0, 0x7149f2ca, v0
	v_add_f32_e32 v0, 1.0, v0
	v_rcp_f32_e32 v166, v0
	v_and_b32_e32 v0, 0xffff0000, v225
	v_mul_f32_e32 v0, 0xbfb8aa3b, v0
	v_exp_f32_e32 v0, v0
	s_nop 0
	v_min_f32_e32 v147, 0x7149f2ca, v0
	v_and_b32_e32 v0, 0xffff0000, v223
	v_mul_f32_e32 v0, 0xbfb8aa3b, v0
	v_exp_f32_e32 v0, v0
	v_pk_add_f32 v[146:147], v[146:147], 1.0 op_sel_hi:[1,0]
	v_min_f32_e32 v0, 0x7149f2ca, v0
	v_add_f32_e32 v0, 1.0, v0
	v_rcp_f32_e32 v167, v0
	s_nop 0
	v_pk_mul_f32 v[146:147], v[146:147], v[166:167]
	s_nop 0
	v_pk_mul_f32 v[14:15], v[14:15], v[146:147]
	s_nop 0
	s_nop 0
	s_nop 0
	s_waitcnt vmcnt(2)
	v_lshlrev_b32_e32 v0, 16, v228
	v_mul_f32_e32 v0, 0xbfb8aa3b, v0
	v_exp_f32_e32 v0, v0
	s_nop 0
	v_min_f32_e32 v168, 0x7149f2ca, v0
	v_lshlrev_b32_e32 v0, 16, v226
	v_mul_f32_e32 v0, 0xbfb8aa3b, v0
	v_exp_f32_e32 v0, v0
	s_nop 0
	v_min_f32_e32 v0, 0x7149f2ca, v0
	v_add_f32_e32 v0, 1.0, v0
	v_rcp_f32_e32 v170, v0
	v_and_b32_e32 v0, 0xffff0000, v228
	v_mul_f32_e32 v0, 0xbfb8aa3b, v0
	v_exp_f32_e32 v0, v0
	s_nop 0
	v_min_f32_e32 v169, 0x7149f2ca, v0
	v_and_b32_e32 v0, 0xffff0000, v226
	v_mul_f32_e32 v0, 0xbfb8aa3b, v0
	v_exp_f32_e32 v0, v0
	v_pk_add_f32 v[168:169], v[168:169], 1.0 op_sel_hi:[1,0]
	v_min_f32_e32 v0, 0x7149f2ca, v0
	v_add_f32_e32 v0, 1.0, v0
	v_rcp_f32_e32 v171, v0
	v_lshlrev_b32_e32 v0, 16, v229
	v_mul_f32_e32 v0, 0xbfb8aa3b, v0
	v_exp_f32_e32 v0, v0
	v_pk_mul_f32 v[168:169], v[168:169], v[170:171]
	v_min_f32_e32 v146, 0x7149f2ca, v0
	v_lshlrev_b32_e32 v0, 16, v227
	v_mul_f32_e32 v0, 0xbfb8aa3b, v0
	v_exp_f32_e32 v0, v0
	v_pk_mul_f32 v[8:9], v[8:9], v[168:169]
	v_min_f32_e32 v0, 0x7149f2ca, v0
	v_add_f32_e32 v0, 1.0, v0
	v_rcp_f32_e32 v166, v0
	v_and_b32_e32 v0, 0xffff0000, v229
	v_mul_f32_e32 v0, 0xbfb8aa3b, v0
	v_exp_f32_e32 v0, v0
	s_nop 0
	v_min_f32_e32 v147, 0x7149f2ca, v0
	v_and_b32_e32 v0, 0xffff0000, v227
	v_mul_f32_e32 v0, 0xbfb8aa3b, v0
	v_exp_f32_e32 v0, v0
	v_pk_add_f32 v[146:147], v[146:147], 1.0 op_sel_hi:[1,0]
	v_min_f32_e32 v0, 0x7149f2ca, v0
	v_add_f32_e32 v0, 1.0, v0
	v_rcp_f32_e32 v167, v0
	s_nop 0
	v_pk_mul_f32 v[146:147], v[146:147], v[166:167]
	s_nop 0
	v_pk_mul_f32 v[10:11], v[10:11], v[146:147]
	s_nop 0
	s_nop 0
	s_nop 0
	s_waitcnt vmcnt(0)
	v_lshlrev_b32_e32 v0, 16, v232
	v_mul_f32_e32 v0, 0xbfb8aa3b, v0
	v_exp_f32_e32 v0, v0
	s_nop 0
	v_min_f32_e32 v146, 0x7149f2ca, v0
	v_lshlrev_b32_e32 v0, 16, v230
	v_mul_f32_e32 v0, 0xbfb8aa3b, v0
	v_exp_f32_e32 v0, v0
	s_nop 0
	v_min_f32_e32 v0, 0x7149f2ca, v0
	v_add_f32_e32 v0, 1.0, v0
	v_rcp_f32_e32 v168, v0
	v_and_b32_e32 v0, 0xffff0000, v232
	v_mul_f32_e32 v0, 0xbfb8aa3b, v0
	v_exp_f32_e32 v0, v0
	s_nop 0
	v_min_f32_e32 v147, 0x7149f2ca, v0
	v_and_b32_e32 v0, 0xffff0000, v230
	v_mul_f32_e32 v0, 0xbfb8aa3b, v0
	v_exp_f32_e32 v0, v0
	v_pk_add_f32 v[146:147], v[146:147], 1.0 op_sel_hi:[1,0]
	v_min_f32_e32 v0, 0x7149f2ca, v0
	v_add_f32_e32 v0, 1.0, v0
	v_rcp_f32_e32 v169, v0
	v_lshlrev_b32_e32 v0, 16, v233
	v_mul_f32_e32 v0, 0xbfb8aa3b, v0
	v_exp_f32_e32 v0, v0
	v_pk_mul_f32 v[146:147], v[146:147], v[168:169]
	v_min_f32_e32 v166, 0x7149f2ca, v0
	v_lshlrev_b32_e32 v0, 16, v231
	v_mul_f32_e32 v0, 0xbfb8aa3b, v0
	v_exp_f32_e32 v0, v0
	v_pk_mul_f32 v[4:5], v[4:5], v[146:147]
	v_min_f32_e32 v0, 0x7149f2ca, v0
	v_add_f32_e32 v0, 1.0, v0
	v_rcp_f32_e32 v2, v0
	v_and_b32_e32 v0, 0xffff0000, v233
	v_mul_f32_e32 v0, 0xbfb8aa3b, v0
	v_exp_f32_e32 v0, v0
	s_nop 0
	v_min_f32_e32 v167, 0x7149f2ca, v0
	v_and_b32_e32 v0, 0xffff0000, v231
	v_mul_f32_e32 v0, 0xbfb8aa3b, v0
	v_exp_f32_e32 v0, v0
	v_pk_add_f32 v[166:167], v[166:167], 1.0 op_sel_hi:[1,0]
	v_min_f32_e32 v0, 0x7149f2ca, v0
	v_add_f32_e32 v0, 1.0, v0
	v_rcp_f32_e32 v3, v0
	s_nop 0
	v_pk_mul_f32 v[2:3], v[166:167], v[2:3]
	s_nop 0
	v_pk_mul_f32 v[6:7], v[6:7], v[2:3]
	s_nop 0

.LBB0_1087:
	v_or_b32_e32 v2, s13, v136
	v_mov_b32_e32 v152, v151
	s_movk_i32 s13, 0x1320
	v_mov_b32_e32 v3, v1
	v_mul_lo_u32 v0, v152, s13
	v_lshl_add_u64 v[144:145], v[0:1], 1, s[8:9]
	v_lshlrev_b64 v[142:143], 1, v[2:3]
	v_lshl_add_u64 v[144:145], v[144:145], 0, v[142:143]
	global_load_dwordx2 v[146:147], v[144:145], off
	global_load_dwordx2 v[198:199], v[144:145], off offset:32
	global_load_dwordx2 v[200:201], v[144:145], off offset:256
	global_load_dwordx2 v[202:203], v[144:145], off offset:288
	v_lshlrev_b32_e32 v156, 10, v152
	s_andn2_b64 vcc, exec, s[6:7]
	s_mov_b64 s[6:7], -1
	s_waitcnt vmcnt(3)
	v_lshlrev_b32_e32 v0, 16, v146
	v_and_b32_e32 v3, 0xffff0000, v146
	v_lshlrev_b32_e32 v146, 16, v147
	v_and_b32_e32 v147, 0xffff0000, v147
	v_mul_f32_e32 v0, 0xbfb8aa3b, v0
	v_mul_f32_e32 v3, 0xbfb8aa3b, v3
	v_mul_f32_e32 v146, 0xbfb8aa3b, v146
	v_mul_f32_e32 v147, 0xbfb8aa3b, v147
	v_exp_f32_e32 v0, v0
	v_exp_f32_e32 v3, v3
	v_exp_f32_e32 v146, v146
	v_exp_f32_e32 v147, v147
	v_min_f32_e32 v0, 0x7149f2ca, v0
	v_min_f32_e32 v3, 0x7149f2ca, v3
	v_min_f32_e32 v146, 0x7149f2ca, v146
	v_min_f32_e32 v147, 0x7149f2ca, v147
	v_add_f32_e32 v0, 1.0, v0
	v_add_f32_e32 v3, 1.0, v3
	v_add_f32_e32 v152, 1.0, v146
	v_add_f32_e32 v153, 1.0, v147
	v_rcp_f32_e32 v146, v0
	v_rcp_f32_e32 v147, v3
	v_rcp_f32_e32 v152, v152
	v_rcp_f32_e32 v153, v153
	v_add_u32_e32 v0, v156, v2
	v_pk_mul_f32 v[128:129], v[128:129], v[146:147]
	v_lshl_add_u64 v[154:155], v[0:1], 1, s[2:3]
	v_pk_mul_f32 v[130:131], v[130:131], v[152:153]
	v_cvt_pk_bf16_f32 v128, v128, v129
	v_cvt_pk_bf16_f32 v129, v130, v131
	global_store_dwordx2 v[154:155], v[128:129], off
	s_nop 0
	v_or_b32_e32 v3, 16, v2
	s_waitcnt vmcnt(3)
	v_lshlrev_b32_e32 v0, 16, v198
	v_and_b32_e32 v128, 0xffff0000, v198
	v_lshlrev_b32_e32 v130, 16, v199
	v_and_b32_e32 v129, 0xffff0000, v199
	v_mul_f32_e32 v0, 0xbfb8aa3b, v0
	v_mul_f32_e32 v128, 0xbfb8aa3b, v128
	v_mul_f32_e32 v130, 0xbfb8aa3b, v130
	v_mul_f32_e32 v129, 0xbfb8aa3b, v129
	v_exp_f32_e32 v0, v0
	v_exp_f32_e32 v128, v128
	v_exp_f32_e32 v130, v130
	v_exp_f32_e32 v129, v129
	v_min_f32_e32 v0, 0x7149f2ca, v0
	v_min_f32_e32 v128, 0x7149f2ca, v128
	v_min_f32_e32 v130, 0x7149f2ca, v130
	v_min_f32_e32 v129, 0x7149f2ca, v129
	v_add_f32_e32 v0, 1.0, v0
	v_add_f32_e32 v131, 1.0, v128
	v_add_f32_e32 v130, 1.0, v130
	v_add_f32_e32 v146, 1.0, v129
	v_rcp_f32_e32 v128, v0
	v_rcp_f32_e32 v129, v131
	v_rcp_f32_e32 v130, v130
	v_rcp_f32_e32 v131, v146
	v_add_u32_e32 v0, v156, v3
	v_pk_mul_f32 v[124:125], v[124:125], v[128:129]
	v_lshl_add_u64 v[146:147], v[0:1], 1, s[2:3]
	v_pk_mul_f32 v[126:127], v[126:127], v[130:131]
	v_cvt_pk_bf16_f32 v124, v124, v125
	v_cvt_pk_bf16_f32 v125, v126, v127
	global_store_dwordx2 v[146:147], v[124:125], off
	s_nop 0
	v_or_b32_e32 v124, 0x80, v2
	s_waitcnt vmcnt(3)
	v_lshlrev_b32_e32 v0, 16, v200
	v_and_b32_e32 v125, 0xffff0000, v200
	v_lshlrev_b32_e32 v126, 16, v201
	v_and_b32_e32 v127, 0xffff0000, v201
	v_mul_f32_e32 v0, 0xbfb8aa3b, v0
	v_mul_f32_e32 v125, 0xbfb8aa3b, v125
	v_mul_f32_e32 v126, 0xbfb8aa3b, v126
	v_mul_f32_e32 v127, 0xbfb8aa3b, v127
	v_exp_f32_e32 v0, v0
	v_exp_f32_e32 v125, v125
	v_exp_f32_e32 v126, v126
	v_exp_f32_e32 v127, v127
	v_min_f32_e32 v0, 0x7149f2ca, v0
	v_min_f32_e32 v125, 0x7149f2ca, v125
	v_min_f32_e32 v126, 0x7149f2ca, v126
	v_min_f32_e32 v127, 0x7149f2ca, v127
	v_add_f32_e32 v0, 1.0, v0
	v_add_f32_e32 v125, 1.0, v125
	v_add_f32_e32 v128, 1.0, v126
	v_add_f32_e32 v129, 1.0, v127
	v_rcp_f32_e32 v126, v0
	v_rcp_f32_e32 v127, v125
	v_rcp_f32_e32 v128, v128
	v_rcp_f32_e32 v129, v129
	v_add_u32_e32 v0, v156, v124
	v_pk_mul_f32 v[120:121], v[120:121], v[126:127]
	v_lshl_add_u64 v[130:131], v[0:1], 1, s[2:3]
	v_pk_mul_f32 v[122:123], v[122:123], v[128:129]
	v_cvt_pk_bf16_f32 v120, v120, v121
	v_cvt_pk_bf16_f32 v121, v122, v123
	global_store_dwordx2 v[130:131], v[120:121], off
	s_nop 0
	v_or_b32_e32 v120, 0x90, v2
	v_or_b32_e32 v121, 16, v151
	s_waitcnt vmcnt(3)
	v_lshlrev_b32_e32 v0, 16, v202
	v_and_b32_e32 v122, 0xffff0000, v202
	v_lshlrev_b32_e32 v125, 16, v203
	v_and_b32_e32 v123, 0xffff0000, v203
	v_mul_f32_e32 v0, 0xbfb8aa3b, v0
	v_mul_f32_e32 v122, 0xbfb8aa3b, v122
	v_mul_f32_e32 v125, 0xbfb8aa3b, v125
	v_mul_f32_e32 v123, 0xbfb8aa3b, v123
	v_exp_f32_e32 v0, v0
	v_exp_f32_e32 v122, v122
	v_exp_f32_e32 v125, v125
	v_exp_f32_e32 v123, v123
	v_min_f32_e32 v0, 0x7149f2ca, v0
	v_min_f32_e32 v122, 0x7149f2ca, v122
	v_min_f32_e32 v125, 0x7149f2ca, v125
	v_min_f32_e32 v123, 0x7149f2ca, v123
	v_add_f32_e32 v0, 1.0, v0
	v_add_f32_e32 v126, 1.0, v122
	v_add_f32_e32 v125, 1.0, v125
	v_add_f32_e32 v127, 1.0, v123
	v_rcp_f32_e32 v122, v0
	v_rcp_f32_e32 v123, v126
	v_rcp_f32_e32 v126, v125
	v_rcp_f32_e32 v127, v127
	v_add_u32_e32 v0, v156, v120
	v_pk_mul_f32 v[116:117], v[116:117], v[122:123]
	v_lshl_add_u64 v[128:129], v[0:1], 1, s[2:3]
	v_pk_mul_f32 v[118:119], v[118:119], v[126:127]
	v_cvt_pk_bf16_f32 v116, v116, v117
	v_cvt_pk_bf16_f32 v117, v118, v119
	global_store_dwordx2 v[128:129], v[116:117], off
	s_nop 0
	v_mul_lo_u32 v0, v121, s13
	v_lshl_add_u64 v[116:117], v[0:1], 1, s[8:9]
	v_lshl_add_u64 v[116:117], v[116:117], 0, v[142:143]
	global_load_dwordx2 v[118:119], v[116:117], off
	global_load_dwordx2 v[198:199], v[116:117], off offset:32
	global_load_dwordx2 v[200:201], v[116:117], off offset:256
	global_load_dwordx2 v[202:203], v[116:117], off offset:288
	v_lshlrev_b32_e32 v121, 10, v121
	s_waitcnt vmcnt(3)
	v_lshlrev_b32_e32 v0, 16, v118
	v_and_b32_e32 v118, 0xffff0000, v118
	v_lshlrev_b32_e32 v122, 16, v119
	v_and_b32_e32 v119, 0xffff0000, v119
	v_mul_f32_e32 v0, 0xbfb8aa3b, v0
	v_mul_f32_e32 v118, 0xbfb8aa3b, v118
	v_mul_f32_e32 v122, 0xbfb8aa3b, v122
	v_mul_f32_e32 v119, 0xbfb8aa3b, v119
	v_exp_f32_e32 v0, v0
	v_exp_f32_e32 v118, v118
	v_exp_f32_e32 v122, v122
	v_exp_f32_e32 v119, v119
	v_min_f32_e32 v0, 0x7149f2ca, v0
	v_min_f32_e32 v118, 0x7149f2ca, v118
	v_min_f32_e32 v122, 0x7149f2ca, v122
	v_min_f32_e32 v119, 0x7149f2ca, v119
	v_add_f32_e32 v0, 1.0, v0
	v_add_f32_e32 v123, 1.0, v118
	v_add_f32_e32 v122, 1.0, v122
	v_add_f32_e32 v125, 1.0, v119
	v_rcp_f32_e32 v118, v0
	v_rcp_f32_e32 v119, v123
	v_rcp_f32_e32 v122, v122
	v_rcp_f32_e32 v123, v125
	v_add_u32_e32 v0, v121, v2
	v_pk_mul_f32 v[112:113], v[112:113], v[118:119]
	v_lshl_add_u64 v[126:127], v[0:1], 1, s[2:3]
	v_pk_mul_f32 v[114:115], v[114:115], v[122:123]
	v_cvt_pk_bf16_f32 v112, v112, v113
	v_cvt_pk_bf16_f32 v113, v114, v115
	global_store_dwordx2 v[126:127], v[112:113], off
	s_nop 0
	s_waitcnt vmcnt(3)
	v_lshlrev_b32_e32 v0, 16, v198
	v_and_b32_e32 v112, 0xffff0000, v198
	v_lshlrev_b32_e32 v114, 16, v199
	v_and_b32_e32 v113, 0xffff0000, v199
	v_mul_f32_e32 v0, 0xbfb8aa3b, v0
	v_mul_f32_e32 v112, 0xbfb8aa3b, v112
	v_mul_f32_e32 v114, 0xbfb8aa3b, v114
	v_mul_f32_e32 v113, 0xbfb8aa3b, v113
	v_exp_f32_e32 v0, v0
	v_exp_f32_e32 v112, v112
	v_exp_f32_e32 v114, v114
	v_exp_f32_e32 v113, v113
	v_min_f32_e32 v0, 0x7149f2ca, v0
	v_min_f32_e32 v112, 0x7149f2ca, v112
	v_min_f32_e32 v114, 0x7149f2ca, v114
	v_min_f32_e32 v113, 0x7149f2ca, v113
	v_add_f32_e32 v0, 1.0, v0
	v_add_f32_e32 v115, 1.0, v112
	v_add_f32_e32 v114, 1.0, v114
	v_add_f32_e32 v118, 1.0, v113
	v_rcp_f32_e32 v112, v0
	v_rcp_f32_e32 v113, v115
	v_rcp_f32_e32 v114, v114
	v_rcp_f32_e32 v115, v118
	v_add_u32_e32 v0, v121, v3
	v_pk_mul_f32 v[108:109], v[108:109], v[112:113]
	v_lshl_add_u64 v[118:119], v[0:1], 1, s[2:3]
	v_pk_mul_f32 v[110:111], v[110:111], v[114:115]
	v_cvt_pk_bf16_f32 v108, v108, v109
	v_cvt_pk_bf16_f32 v109, v110, v111
	global_store_dwordx2 v[118:119], v[108:109], off
	s_nop 0
	s_waitcnt vmcnt(3)
	v_lshlrev_b32_e32 v0, 16, v200
	v_and_b32_e32 v108, 0xffff0000, v200
	v_lshlrev_b32_e32 v110, 16, v201
	v_and_b32_e32 v109, 0xffff0000, v201
	v_mul_f32_e32 v0, 0xbfb8aa3b, v0
	v_mul_f32_e32 v108, 0xbfb8aa3b, v108
	v_mul_f32_e32 v110, 0xbfb8aa3b, v110
	v_mul_f32_e32 v109, 0xbfb8aa3b, v109
	v_exp_f32_e32 v0, v0
	v_exp_f32_e32 v108, v108
	v_exp_f32_e32 v110, v110
	v_exp_f32_e32 v109, v109
	v_min_f32_e32 v0, 0x7149f2ca, v0
	v_min_f32_e32 v108, 0x7149f2ca, v108
	v_min_f32_e32 v110, 0x7149f2ca, v110
	v_min_f32_e32 v109, 0x7149f2ca, v109
	v_add_f32_e32 v0, 1.0, v0
	v_add_f32_e32 v111, 1.0, v108
	v_add_f32_e32 v110, 1.0, v110
	v_add_f32_e32 v112, 1.0, v109
	v_rcp_f32_e32 v108, v0
	v_rcp_f32_e32 v109, v111
	v_rcp_f32_e32 v110, v110
	v_rcp_f32_e32 v111, v112
	v_add_u32_e32 v0, v121, v124
	v_pk_mul_f32 v[104:105], v[104:105], v[108:109]
	v_lshl_add_u64 v[112:113], v[0:1], 1, s[2:3]
	v_pk_mul_f32 v[106:107], v[106:107], v[110:111]
	v_cvt_pk_bf16_f32 v104, v104, v105
	v_cvt_pk_bf16_f32 v105, v106, v107
	global_store_dwordx2 v[112:113], v[104:105], off
	s_nop 0
	v_or_b32_e32 v110, 32, v151
	s_waitcnt vmcnt(3)
	v_lshlrev_b32_e32 v0, 16, v202
	v_and_b32_e32 v104, 0xffff0000, v202
	v_lshlrev_b32_e32 v106, 16, v203
	v_and_b32_e32 v105, 0xffff0000, v203
	v_mul_f32_e32 v0, 0xbfb8aa3b, v0
	v_mul_f32_e32 v104, 0xbfb8aa3b, v104
	v_mul_f32_e32 v106, 0xbfb8aa3b, v106
	v_mul_f32_e32 v105, 0xbfb8aa3b, v105
	v_exp_f32_e32 v0, v0
	v_exp_f32_e32 v104, v104
	v_exp_f32_e32 v106, v106
	v_exp_f32_e32 v105, v105
	v_min_f32_e32 v0, 0x7149f2ca, v0
	v_min_f32_e32 v104, 0x7149f2ca, v104
	v_min_f32_e32 v106, 0x7149f2ca, v106
	v_min_f32_e32 v105, 0x7149f2ca, v105
	v_add_f32_e32 v0, 1.0, v0
	v_add_f32_e32 v107, 1.0, v104
	v_add_f32_e32 v106, 1.0, v106
	v_add_f32_e32 v108, 1.0, v105
	v_rcp_f32_e32 v104, v0
	v_rcp_f32_e32 v105, v107
	v_rcp_f32_e32 v106, v106
	v_rcp_f32_e32 v107, v108
	v_add_u32_e32 v0, v121, v120
	v_pk_mul_f32 v[100:101], v[100:101], v[104:105]
	v_lshl_add_u64 v[108:109], v[0:1], 1, s[2:3]
	v_pk_mul_f32 v[102:103], v[102:103], v[106:107]
	v_cvt_pk_bf16_f32 v100, v100, v101
	v_cvt_pk_bf16_f32 v101, v102, v103
	global_store_dwordx2 v[108:109], v[100:101], off
	s_nop 0
	v_mul_lo_u32 v0, v110, s13
	v_lshl_add_u64 v[100:101], v[0:1], 1, s[8:9]
	v_lshl_add_u64 v[100:101], v[100:101], 0, v[142:143]
	global_load_dwordx2 v[102:103], v[100:101], off
	global_load_dwordx2 v[198:199], v[100:101], off offset:32
	global_load_dwordx2 v[200:201], v[100:101], off offset:256
	global_load_dwordx2 v[202:203], v[100:101], off offset:288
	v_lshlrev_b32_e32 v108, 10, v110
	s_waitcnt vmcnt(3)
	v_lshlrev_b32_e32 v0, 16, v102
	v_and_b32_e32 v102, 0xffff0000, v102
	v_lshlrev_b32_e32 v104, 16, v103
	v_and_b32_e32 v103, 0xffff0000, v103
	v_mul_f32_e32 v0, 0xbfb8aa3b, v0
	v_mul_f32_e32 v102, 0xbfb8aa3b, v102
	v_mul_f32_e32 v104, 0xbfb8aa3b, v104
	v_mul_f32_e32 v103, 0xbfb8aa3b, v103
	v_exp_f32_e32 v0, v0
	v_exp_f32_e32 v102, v102
	v_exp_f32_e32 v104, v104
	v_exp_f32_e32 v103, v103
	v_min_f32_e32 v0, 0x7149f2ca, v0
	v_min_f32_e32 v102, 0x7149f2ca, v102
	v_min_f32_e32 v104, 0x7149f2ca, v104
	v_min_f32_e32 v103, 0x7149f2ca, v103
	v_add_f32_e32 v0, 1.0, v0
	v_add_f32_e32 v105, 1.0, v102
	v_add_f32_e32 v104, 1.0, v104
	v_add_f32_e32 v106, 1.0, v103
	v_rcp_f32_e32 v102, v0
	v_rcp_f32_e32 v103, v105
	v_rcp_f32_e32 v104, v104
	v_rcp_f32_e32 v105, v106
	v_add_u32_e32 v0, v108, v2
	v_pk_mul_f32 v[96:97], v[96:97], v[102:103]
	v_lshl_add_u64 v[106:107], v[0:1], 1, s[2:3]
	v_pk_mul_f32 v[98:99], v[98:99], v[104:105]
	v_cvt_pk_bf16_f32 v96, v96, v97
	v_cvt_pk_bf16_f32 v97, v98, v99
	global_store_dwordx2 v[106:107], v[96:97], off
	s_nop 0
	s_waitcnt vmcnt(3)
	v_lshlrev_b32_e32 v0, 16, v198
	v_and_b32_e32 v96, 0xffff0000, v198
	v_lshlrev_b32_e32 v98, 16, v199
	v_and_b32_e32 v97, 0xffff0000, v199
	v_mul_f32_e32 v0, 0xbfb8aa3b, v0
	v_mul_f32_e32 v96, 0xbfb8aa3b, v96
	v_mul_f32_e32 v98, 0xbfb8aa3b, v98
	v_mul_f32_e32 v97, 0xbfb8aa3b, v97
	v_exp_f32_e32 v0, v0
	v_exp_f32_e32 v96, v96
	v_exp_f32_e32 v98, v98
	v_exp_f32_e32 v97, v97
	v_min_f32_e32 v0, 0x7149f2ca, v0
	v_min_f32_e32 v96, 0x7149f2ca, v96
	v_min_f32_e32 v98, 0x7149f2ca, v98
	v_min_f32_e32 v97, 0x7149f2ca, v97
	v_add_f32_e32 v0, 1.0, v0
	v_add_f32_e32 v99, 1.0, v96
	v_add_f32_e32 v98, 1.0, v98
	v_add_f32_e32 v102, 1.0, v97
	v_rcp_f32_e32 v96, v0
	v_rcp_f32_e32 v97, v99
	v_rcp_f32_e32 v98, v98
	v_rcp_f32_e32 v99, v102
	v_add_u32_e32 v0, v108, v3
	v_pk_mul_f32 v[92:93], v[92:93], v[96:97]
	v_lshl_add_u64 v[102:103], v[0:1], 1, s[2:3]
	v_pk_mul_f32 v[94:95], v[94:95], v[98:99]
	v_cvt_pk_bf16_f32 v92, v92, v93
	v_cvt_pk_bf16_f32 v93, v94, v95
	global_store_dwordx2 v[102:103], v[92:93], off
	s_nop 0
	s_waitcnt vmcnt(3)
	v_lshlrev_b32_e32 v0, 16, v200
	v_and_b32_e32 v92, 0xffff0000, v200
	v_lshlrev_b32_e32 v94, 16, v201
	v_and_b32_e32 v93, 0xffff0000, v201
	v_mul_f32_e32 v0, 0xbfb8aa3b, v0
	v_mul_f32_e32 v92, 0xbfb8aa3b, v92
	v_mul_f32_e32 v94, 0xbfb8aa3b, v94
	v_mul_f32_e32 v93, 0xbfb8aa3b, v93
	v_exp_f32_e32 v0, v0
	v_exp_f32_e32 v92, v92
	v_exp_f32_e32 v94, v94
	v_exp_f32_e32 v93, v93
	v_min_f32_e32 v0, 0x7149f2ca, v0
	v_min_f32_e32 v92, 0x7149f2ca, v92
	v_min_f32_e32 v94, 0x7149f2ca, v94
	v_min_f32_e32 v93, 0x7149f2ca, v93
	v_add_f32_e32 v0, 1.0, v0
	v_add_f32_e32 v95, 1.0, v92
	v_add_f32_e32 v94, 1.0, v94
	v_add_f32_e32 v96, 1.0, v93
	v_rcp_f32_e32 v92, v0
	v_rcp_f32_e32 v93, v95
	v_rcp_f32_e32 v94, v94
	v_rcp_f32_e32 v95, v96
	v_add_u32_e32 v0, v108, v124
	v_pk_mul_f32 v[88:89], v[88:89], v[92:93]
	v_lshl_add_u64 v[96:97], v[0:1], 1, s[2:3]
	v_pk_mul_f32 v[90:91], v[90:91], v[94:95]
	v_cvt_pk_bf16_f32 v88, v88, v89
	v_cvt_pk_bf16_f32 v89, v90, v91
	global_store_dwordx2 v[96:97], v[88:89], off
	s_nop 0
	v_or_b32_e32 v94, 48, v151
	s_waitcnt vmcnt(3)
	v_lshlrev_b32_e32 v0, 16, v202
	v_and_b32_e32 v88, 0xffff0000, v202
	v_lshlrev_b32_e32 v90, 16, v203
	v_and_b32_e32 v89, 0xffff0000, v203
	v_mul_f32_e32 v0, 0xbfb8aa3b, v0
	v_mul_f32_e32 v88, 0xbfb8aa3b, v88
	v_mul_f32_e32 v90, 0xbfb8aa3b, v90
	v_mul_f32_e32 v89, 0xbfb8aa3b, v89
	v_exp_f32_e32 v0, v0
	v_exp_f32_e32 v88, v88
	v_exp_f32_e32 v90, v90
	v_exp_f32_e32 v89, v89
	v_min_f32_e32 v0, 0x7149f2ca, v0
	v_min_f32_e32 v88, 0x7149f2ca, v88
	v_min_f32_e32 v90, 0x7149f2ca, v90
	v_min_f32_e32 v89, 0x7149f2ca, v89
	v_add_f32_e32 v0, 1.0, v0
	v_add_f32_e32 v91, 1.0, v88
	v_add_f32_e32 v90, 1.0, v90
	v_add_f32_e32 v92, 1.0, v89
	v_rcp_f32_e32 v88, v0
	v_rcp_f32_e32 v89, v91
	v_rcp_f32_e32 v90, v90
	v_rcp_f32_e32 v91, v92
	v_add_u32_e32 v0, v108, v120
	v_pk_mul_f32 v[84:85], v[84:85], v[88:89]
	v_lshl_add_u64 v[92:93], v[0:1], 1, s[2:3]
	v_pk_mul_f32 v[86:87], v[86:87], v[90:91]
	v_cvt_pk_bf16_f32 v84, v84, v85
	v_cvt_pk_bf16_f32 v85, v86, v87
	global_store_dwordx2 v[92:93], v[84:85], off
	s_nop 0
	v_mul_lo_u32 v0, v94, s13
	v_lshl_add_u64 v[84:85], v[0:1], 1, s[8:9]
	v_lshl_add_u64 v[84:85], v[84:85], 0, v[142:143]
	global_load_dwordx2 v[86:87], v[84:85], off
	global_load_dwordx2 v[198:199], v[84:85], off offset:32
	global_load_dwordx2 v[200:201], v[84:85], off offset:256
	global_load_dwordx2 v[202:203], v[84:85], off offset:288
	v_lshlrev_b32_e32 v92, 10, v94
	s_waitcnt vmcnt(3)
	v_lshlrev_b32_e32 v0, 16, v86
	v_and_b32_e32 v86, 0xffff0000, v86
	v_lshlrev_b32_e32 v88, 16, v87
	v_and_b32_e32 v87, 0xffff0000, v87
	v_mul_f32_e32 v0, 0xbfb8aa3b, v0
	v_mul_f32_e32 v86, 0xbfb8aa3b, v86
	v_mul_f32_e32 v88, 0xbfb8aa3b, v88
	v_mul_f32_e32 v87, 0xbfb8aa3b, v87
	v_exp_f32_e32 v0, v0
	v_exp_f32_e32 v86, v86
	v_exp_f32_e32 v88, v88
	v_exp_f32_e32 v87, v87
	v_min_f32_e32 v0, 0x7149f2ca, v0
	v_min_f32_e32 v86, 0x7149f2ca, v86
	v_min_f32_e32 v88, 0x7149f2ca, v88
	v_min_f32_e32 v87, 0x7149f2ca, v87
	v_add_f32_e32 v0, 1.0, v0
	v_add_f32_e32 v89, 1.0, v86
	v_add_f32_e32 v88, 1.0, v88
	v_add_f32_e32 v90, 1.0, v87
	v_rcp_f32_e32 v86, v0
	v_rcp_f32_e32 v87, v89
	v_rcp_f32_e32 v88, v88
	v_rcp_f32_e32 v89, v90
	v_add_u32_e32 v0, v92, v2
	v_pk_mul_f32 v[80:81], v[80:81], v[86:87]
	v_lshl_add_u64 v[90:91], v[0:1], 1, s[2:3]
	v_pk_mul_f32 v[82:83], v[82:83], v[88:89]
	v_cvt_pk_bf16_f32 v80, v80, v81
	v_cvt_pk_bf16_f32 v81, v82, v83
	global_store_dwordx2 v[90:91], v[80:81], off
	s_nop 0
	s_waitcnt vmcnt(3)
	v_lshlrev_b32_e32 v0, 16, v198
	v_and_b32_e32 v80, 0xffff0000, v198
	v_lshlrev_b32_e32 v82, 16, v199
	v_and_b32_e32 v81, 0xffff0000, v199
	v_mul_f32_e32 v0, 0xbfb8aa3b, v0
	v_mul_f32_e32 v80, 0xbfb8aa3b, v80
	v_mul_f32_e32 v82, 0xbfb8aa3b, v82
	v_mul_f32_e32 v81, 0xbfb8aa3b, v81
	v_exp_f32_e32 v0, v0
	v_exp_f32_e32 v80, v80
	v_exp_f32_e32 v82, v82
	v_exp_f32_e32 v81, v81
	v_min_f32_e32 v0, 0x7149f2ca, v0
	v_min_f32_e32 v80, 0x7149f2ca, v80
	v_min_f32_e32 v82, 0x7149f2ca, v82
	v_min_f32_e32 v81, 0x7149f2ca, v81
	v_add_f32_e32 v0, 1.0, v0
	v_add_f32_e32 v83, 1.0, v80
	v_add_f32_e32 v82, 1.0, v82
	v_add_f32_e32 v86, 1.0, v81
	v_rcp_f32_e32 v80, v0
	v_rcp_f32_e32 v81, v83
	v_rcp_f32_e32 v82, v82
	v_rcp_f32_e32 v83, v86
	v_add_u32_e32 v0, v92, v3
	v_pk_mul_f32 v[76:77], v[76:77], v[80:81]
	v_lshl_add_u64 v[86:87], v[0:1], 1, s[2:3]
	v_pk_mul_f32 v[78:79], v[78:79], v[82:83]
	v_cvt_pk_bf16_f32 v76, v76, v77
	v_cvt_pk_bf16_f32 v77, v78, v79
	global_store_dwordx2 v[86:87], v[76:77], off
	s_nop 0
	s_waitcnt vmcnt(3)
	v_lshlrev_b32_e32 v0, 16, v200
	v_and_b32_e32 v76, 0xffff0000, v200
	v_lshlrev_b32_e32 v78, 16, v201
	v_and_b32_e32 v77, 0xffff0000, v201
	v_mul_f32_e32 v0, 0xbfb8aa3b, v0
	v_mul_f32_e32 v76, 0xbfb8aa3b, v76
	v_mul_f32_e32 v78, 0xbfb8aa3b, v78
	v_mul_f32_e32 v77, 0xbfb8aa3b, v77
	v_exp_f32_e32 v0, v0
	v_exp_f32_e32 v76, v76
	v_exp_f32_e32 v78, v78
	v_exp_f32_e32 v77, v77
	v_min_f32_e32 v0, 0x7149f2ca, v0
	v_min_f32_e32 v76, 0x7149f2ca, v76
	v_min_f32_e32 v78, 0x7149f2ca, v78
	v_min_f32_e32 v77, 0x7149f2ca, v77
	v_add_f32_e32 v0, 1.0, v0
	v_add_f32_e32 v79, 1.0, v76
	v_add_f32_e32 v78, 1.0, v78
	v_add_f32_e32 v80, 1.0, v77
	v_rcp_f32_e32 v76, v0
	v_rcp_f32_e32 v77, v79
	v_rcp_f32_e32 v78, v78
	v_rcp_f32_e32 v79, v80
	v_add_u32_e32 v0, v92, v124
	v_pk_mul_f32 v[72:73], v[72:73], v[76:77]
	v_lshl_add_u64 v[80:81], v[0:1], 1, s[2:3]
	v_pk_mul_f32 v[74:75], v[74:75], v[78:79]
	v_cvt_pk_bf16_f32 v72, v72, v73
	v_cvt_pk_bf16_f32 v73, v74, v75
	global_store_dwordx2 v[80:81], v[72:73], off
	s_nop 0
	v_add_u32_e32 v78, 0x80, v151
	s_waitcnt vmcnt(3)
	v_lshlrev_b32_e32 v0, 16, v202
	v_and_b32_e32 v72, 0xffff0000, v202
	v_lshlrev_b32_e32 v74, 16, v203
	v_and_b32_e32 v73, 0xffff0000, v203
	v_mul_f32_e32 v0, 0xbfb8aa3b, v0
	v_mul_f32_e32 v72, 0xbfb8aa3b, v72
	v_mul_f32_e32 v74, 0xbfb8aa3b, v74
	v_mul_f32_e32 v73, 0xbfb8aa3b, v73
	v_exp_f32_e32 v0, v0
	v_exp_f32_e32 v72, v72
	v_exp_f32_e32 v74, v74
	v_exp_f32_e32 v73, v73
	v_min_f32_e32 v0, 0x7149f2ca, v0
	v_min_f32_e32 v72, 0x7149f2ca, v72
	v_min_f32_e32 v74, 0x7149f2ca, v74
	v_min_f32_e32 v73, 0x7149f2ca, v73
	v_add_f32_e32 v0, 1.0, v0
	v_add_f32_e32 v75, 1.0, v72
	v_add_f32_e32 v74, 1.0, v74
	v_add_f32_e32 v76, 1.0, v73
	v_rcp_f32_e32 v72, v0
	v_rcp_f32_e32 v73, v75
	v_rcp_f32_e32 v74, v74
	v_rcp_f32_e32 v75, v76
	v_add_u32_e32 v0, v92, v120
	v_pk_mul_f32 v[68:69], v[68:69], v[72:73]
	v_lshl_add_u64 v[76:77], v[0:1], 1, s[2:3]
	v_pk_mul_f32 v[70:71], v[70:71], v[74:75]
	v_cvt_pk_bf16_f32 v68, v68, v69
	v_cvt_pk_bf16_f32 v69, v70, v71
	global_store_dwordx2 v[76:77], v[68:69], off
	s_nop 0
	v_mul_lo_u32 v0, v78, s13
	v_lshl_add_u64 v[68:69], v[0:1], 1, s[8:9]
	v_lshl_add_u64 v[68:69], v[68:69], 0, v[142:143]
	global_load_dwordx2 v[70:71], v[68:69], off
	global_load_dwordx2 v[198:199], v[68:69], off offset:32
	global_load_dwordx2 v[200:201], v[68:69], off offset:256
	global_load_dwordx2 v[202:203], v[68:69], off offset:288
	v_lshlrev_b32_e32 v76, 10, v78
	s_waitcnt vmcnt(3)
	v_lshlrev_b32_e32 v0, 16, v70
	v_and_b32_e32 v70, 0xffff0000, v70
	v_lshlrev_b32_e32 v72, 16, v71
	v_and_b32_e32 v71, 0xffff0000, v71
	v_mul_f32_e32 v0, 0xbfb8aa3b, v0
	v_mul_f32_e32 v70, 0xbfb8aa3b, v70
	v_mul_f32_e32 v72, 0xbfb8aa3b, v72
	v_mul_f32_e32 v71, 0xbfb8aa3b, v71
	v_exp_f32_e32 v0, v0
	v_exp_f32_e32 v70, v70
	v_exp_f32_e32 v72, v72
	v_exp_f32_e32 v71, v71
	v_min_f32_e32 v0, 0x7149f2ca, v0
	v_min_f32_e32 v70, 0x7149f2ca, v70
	v_min_f32_e32 v72, 0x7149f2ca, v72
	v_min_f32_e32 v71, 0x7149f2ca, v71
	v_add_f32_e32 v0, 1.0, v0
	v_add_f32_e32 v73, 1.0, v70
	v_add_f32_e32 v72, 1.0, v72
	v_add_f32_e32 v74, 1.0, v71
	v_rcp_f32_e32 v70, v0
	v_rcp_f32_e32 v71, v73
	v_rcp_f32_e32 v72, v72
	v_rcp_f32_e32 v73, v74
	v_add_u32_e32 v0, v76, v2
	v_pk_mul_f32 v[64:65], v[64:65], v[70:71]
	v_lshl_add_u64 v[74:75], v[0:1], 1, s[2:3]
	v_pk_mul_f32 v[66:67], v[66:67], v[72:73]
	v_cvt_pk_bf16_f32 v64, v64, v65
	v_cvt_pk_bf16_f32 v65, v66, v67
	global_store_dwordx2 v[74:75], v[64:65], off
	s_nop 0
	s_waitcnt vmcnt(3)
	v_lshlrev_b32_e32 v0, 16, v198
	v_and_b32_e32 v64, 0xffff0000, v198
	v_lshlrev_b32_e32 v66, 16, v199
	v_and_b32_e32 v65, 0xffff0000, v199
	v_mul_f32_e32 v0, 0xbfb8aa3b, v0
	v_mul_f32_e32 v64, 0xbfb8aa3b, v64
	v_mul_f32_e32 v66, 0xbfb8aa3b, v66
	v_mul_f32_e32 v65, 0xbfb8aa3b, v65
	v_exp_f32_e32 v0, v0
	v_exp_f32_e32 v64, v64
	v_exp_f32_e32 v66, v66
	v_exp_f32_e32 v65, v65
	v_min_f32_e32 v0, 0x7149f2ca, v0
	v_min_f32_e32 v64, 0x7149f2ca, v64
	v_min_f32_e32 v66, 0x7149f2ca, v66
	v_min_f32_e32 v65, 0x7149f2ca, v65
	v_add_f32_e32 v0, 1.0, v0
	v_add_f32_e32 v67, 1.0, v64
	v_add_f32_e32 v66, 1.0, v66
	v_add_f32_e32 v70, 1.0, v65
	v_rcp_f32_e32 v64, v0
	v_rcp_f32_e32 v65, v67
	v_rcp_f32_e32 v66, v66
	v_rcp_f32_e32 v67, v70
	v_add_u32_e32 v0, v76, v3
	v_pk_mul_f32 v[60:61], v[60:61], v[64:65]
	v_lshl_add_u64 v[70:71], v[0:1], 1, s[2:3]
	v_pk_mul_f32 v[62:63], v[62:63], v[66:67]
	v_cvt_pk_bf16_f32 v60, v60, v61
	v_cvt_pk_bf16_f32 v61, v62, v63
	global_store_dwordx2 v[70:71], v[60:61], off
	s_nop 0
	s_waitcnt vmcnt(3)
	v_lshlrev_b32_e32 v0, 16, v200
	v_and_b32_e32 v60, 0xffff0000, v200
	v_lshlrev_b32_e32 v62, 16, v201
	v_and_b32_e32 v61, 0xffff0000, v201
	v_mul_f32_e32 v0, 0xbfb8aa3b, v0
	v_mul_f32_e32 v60, 0xbfb8aa3b, v60
	v_mul_f32_e32 v62, 0xbfb8aa3b, v62
	v_mul_f32_e32 v61, 0xbfb8aa3b, v61
	v_exp_f32_e32 v0, v0
	v_exp_f32_e32 v60, v60
	v_exp_f32_e32 v62, v62
	v_exp_f32_e32 v61, v61
	v_min_f32_e32 v0, 0x7149f2ca, v0
	v_min_f32_e32 v60, 0x7149f2ca, v60
	v_min_f32_e32 v62, 0x7149f2ca, v62
	v_min_f32_e32 v61, 0x7149f2ca, v61
	v_add_f32_e32 v0, 1.0, v0
	v_add_f32_e32 v63, 1.0, v60
	v_add_f32_e32 v62, 1.0, v62
	v_add_f32_e32 v64, 1.0, v61
	v_rcp_f32_e32 v60, v0
	v_rcp_f32_e32 v61, v63
	v_rcp_f32_e32 v62, v62
	v_rcp_f32_e32 v63, v64
	v_add_u32_e32 v0, v76, v124
	v_pk_mul_f32 v[56:57], v[56:57], v[60:61]
	v_lshl_add_u64 v[64:65], v[0:1], 1, s[2:3]
	v_pk_mul_f32 v[58:59], v[58:59], v[62:63]
	v_cvt_pk_bf16_f32 v56, v56, v57
	v_cvt_pk_bf16_f32 v57, v58, v59
	global_store_dwordx2 v[64:65], v[56:57], off
	s_nop 0
	v_add_u32_e32 v62, 0x90, v151
	s_waitcnt vmcnt(3)
	v_lshlrev_b32_e32 v0, 16, v202
	v_and_b32_e32 v56, 0xffff0000, v202
	v_lshlrev_b32_e32 v58, 16, v203
	v_and_b32_e32 v57, 0xffff0000, v203
	v_mul_f32_e32 v0, 0xbfb8aa3b, v0
	v_mul_f32_e32 v56, 0xbfb8aa3b, v56
	v_mul_f32_e32 v58, 0xbfb8aa3b, v58
	v_mul_f32_e32 v57, 0xbfb8aa3b, v57
	v_exp_f32_e32 v0, v0
	v_exp_f32_e32 v56, v56
	v_exp_f32_e32 v58, v58
	v_exp_f32_e32 v57, v57
	v_min_f32_e32 v0, 0x7149f2ca, v0
	v_min_f32_e32 v56, 0x7149f2ca, v56
	v_min_f32_e32 v58, 0x7149f2ca, v58
	v_min_f32_e32 v57, 0x7149f2ca, v57
	v_add_f32_e32 v0, 1.0, v0
	v_add_f32_e32 v59, 1.0, v56
	v_add_f32_e32 v58, 1.0, v58
	v_add_f32_e32 v60, 1.0, v57
	v_rcp_f32_e32 v56, v0
	v_rcp_f32_e32 v57, v59
	v_rcp_f32_e32 v58, v58
	v_rcp_f32_e32 v59, v60
	v_add_u32_e32 v0, v76, v120
	v_pk_mul_f32 v[52:53], v[52:53], v[56:57]
	v_lshl_add_u64 v[60:61], v[0:1], 1, s[2:3]
	v_pk_mul_f32 v[54:55], v[54:55], v[58:59]
	v_cvt_pk_bf16_f32 v52, v52, v53
	v_cvt_pk_bf16_f32 v53, v54, v55
	global_store_dwordx2 v[60:61], v[52:53], off
	s_nop 0
	v_mul_lo_u32 v0, v62, s13
	v_lshl_add_u64 v[52:53], v[0:1], 1, s[8:9]
	v_lshl_add_u64 v[52:53], v[52:53], 0, v[142:143]
	global_load_dwordx2 v[54:55], v[52:53], off
	global_load_dwordx2 v[198:199], v[52:53], off offset:32
	global_load_dwordx2 v[200:201], v[52:53], off offset:256
	global_load_dwordx2 v[202:203], v[52:53], off offset:288
	v_lshlrev_b32_e32 v60, 10, v62
	s_waitcnt vmcnt(3)
	v_lshlrev_b32_e32 v0, 16, v54
	v_and_b32_e32 v54, 0xffff0000, v54
	v_lshlrev_b32_e32 v56, 16, v55
	v_and_b32_e32 v55, 0xffff0000, v55
	v_mul_f32_e32 v0, 0xbfb8aa3b, v0
	v_mul_f32_e32 v54, 0xbfb8aa3b, v54
	v_mul_f32_e32 v56, 0xbfb8aa3b, v56
	v_mul_f32_e32 v55, 0xbfb8aa3b, v55
	v_exp_f32_e32 v0, v0
	v_exp_f32_e32 v54, v54
	v_exp_f32_e32 v56, v56
	v_exp_f32_e32 v55, v55
	v_min_f32_e32 v0, 0x7149f2ca, v0
	v_min_f32_e32 v54, 0x7149f2ca, v54
	v_min_f32_e32 v56, 0x7149f2ca, v56
	v_min_f32_e32 v55, 0x7149f2ca, v55
	v_add_f32_e32 v0, 1.0, v0
	v_add_f32_e32 v57, 1.0, v54
	v_add_f32_e32 v56, 1.0, v56
	v_add_f32_e32 v58, 1.0, v55
	v_rcp_f32_e32 v54, v0
	v_rcp_f32_e32 v55, v57
	v_rcp_f32_e32 v56, v56
	v_rcp_f32_e32 v57, v58
	v_add_u32_e32 v0, v60, v2
	v_pk_mul_f32 v[48:49], v[48:49], v[54:55]
	v_lshl_add_u64 v[58:59], v[0:1], 1, s[2:3]
	v_pk_mul_f32 v[50:51], v[50:51], v[56:57]
	v_cvt_pk_bf16_f32 v48, v48, v49
	v_cvt_pk_bf16_f32 v49, v50, v51
	global_store_dwordx2 v[58:59], v[48:49], off
	s_nop 0
	s_waitcnt vmcnt(3)
	v_lshlrev_b32_e32 v0, 16, v198
	v_and_b32_e32 v48, 0xffff0000, v198
	v_lshlrev_b32_e32 v50, 16, v199
	v_and_b32_e32 v49, 0xffff0000, v199
	v_mul_f32_e32 v0, 0xbfb8aa3b, v0
	v_mul_f32_e32 v48, 0xbfb8aa3b, v48
	v_mul_f32_e32 v50, 0xbfb8aa3b, v50
	v_mul_f32_e32 v49, 0xbfb8aa3b, v49
	v_exp_f32_e32 v0, v0
	v_exp_f32_e32 v48, v48
	v_exp_f32_e32 v50, v50
	v_exp_f32_e32 v49, v49
	v_min_f32_e32 v0, 0x7149f2ca, v0
	v_min_f32_e32 v48, 0x7149f2ca, v48
	v_min_f32_e32 v50, 0x7149f2ca, v50
	v_min_f32_e32 v49, 0x7149f2ca, v49
	v_add_f32_e32 v0, 1.0, v0
	v_add_f32_e32 v51, 1.0, v48
	v_add_f32_e32 v50, 1.0, v50
	v_add_f32_e32 v54, 1.0, v49
	v_rcp_f32_e32 v48, v0
	v_rcp_f32_e32 v49, v51
	v_rcp_f32_e32 v50, v50
	v_rcp_f32_e32 v51, v54
	v_add_u32_e32 v0, v60, v3
	v_pk_mul_f32 v[44:45], v[44:45], v[48:49]
	v_lshl_add_u64 v[54:55], v[0:1], 1, s[2:3]
	v_pk_mul_f32 v[46:47], v[46:47], v[50:51]
	v_cvt_pk_bf16_f32 v44, v44, v45
	v_cvt_pk_bf16_f32 v45, v46, v47
	global_store_dwordx2 v[54:55], v[44:45], off
	s_nop 0
	s_waitcnt vmcnt(3)
	v_lshlrev_b32_e32 v0, 16, v200
	v_and_b32_e32 v44, 0xffff0000, v200
	v_lshlrev_b32_e32 v46, 16, v201
	v_and_b32_e32 v45, 0xffff0000, v201
	v_mul_f32_e32 v0, 0xbfb8aa3b, v0
	v_mul_f32_e32 v44, 0xbfb8aa3b, v44
	v_mul_f32_e32 v46, 0xbfb8aa3b, v46
	v_mul_f32_e32 v45, 0xbfb8aa3b, v45
	v_exp_f32_e32 v0, v0
	v_exp_f32_e32 v44, v44
	v_exp_f32_e32 v46, v46
	v_exp_f32_e32 v45, v45
	v_min_f32_e32 v0, 0x7149f2ca, v0
	v_min_f32_e32 v44, 0x7149f2ca, v44
	v_min_f32_e32 v46, 0x7149f2ca, v46
	v_min_f32_e32 v45, 0x7149f2ca, v45
	v_add_f32_e32 v0, 1.0, v0
	v_add_f32_e32 v47, 1.0, v44
	v_add_f32_e32 v46, 1.0, v46
	v_add_f32_e32 v48, 1.0, v45
	v_rcp_f32_e32 v44, v0
	v_rcp_f32_e32 v45, v47
	v_rcp_f32_e32 v46, v46
	v_rcp_f32_e32 v47, v48
	v_add_u32_e32 v0, v60, v124
	v_pk_mul_f32 v[40:41], v[40:41], v[44:45]
	v_lshl_add_u64 v[48:49], v[0:1], 1, s[2:3]
	v_pk_mul_f32 v[42:43], v[42:43], v[46:47]
	v_cvt_pk_bf16_f32 v40, v40, v41
	v_cvt_pk_bf16_f32 v41, v42, v43
	global_store_dwordx2 v[48:49], v[40:41], off
	s_nop 0
	v_add_u32_e32 v46, 0xa0, v151
	s_waitcnt vmcnt(3)
	v_lshlrev_b32_e32 v0, 16, v202
	v_and_b32_e32 v40, 0xffff0000, v202
	v_lshlrev_b32_e32 v42, 16, v203
	v_and_b32_e32 v41, 0xffff0000, v203
	v_mul_f32_e32 v0, 0xbfb8aa3b, v0
	v_mul_f32_e32 v40, 0xbfb8aa3b, v40
	v_mul_f32_e32 v42, 0xbfb8aa3b, v42
	v_mul_f32_e32 v41, 0xbfb8aa3b, v41
	v_exp_f32_e32 v0, v0
	v_exp_f32_e32 v40, v40
	v_exp_f32_e32 v42, v42
	v_exp_f32_e32 v41, v41
	v_min_f32_e32 v0, 0x7149f2ca, v0
	v_min_f32_e32 v40, 0x7149f2ca, v40
	v_min_f32_e32 v42, 0x7149f2ca, v42
	v_min_f32_e32 v41, 0x7149f2ca, v41
	v_add_f32_e32 v0, 1.0, v0
	v_add_f32_e32 v43, 1.0, v40
	v_add_f32_e32 v42, 1.0, v42
	v_add_f32_e32 v44, 1.0, v41
	v_rcp_f32_e32 v40, v0
	v_rcp_f32_e32 v41, v43
	v_rcp_f32_e32 v42, v42
	v_rcp_f32_e32 v43, v44
	v_add_u32_e32 v0, v60, v120
	v_pk_mul_f32 v[36:37], v[36:37], v[40:41]
	v_lshl_add_u64 v[44:45], v[0:1], 1, s[2:3]
	v_pk_mul_f32 v[38:39], v[38:39], v[42:43]
	v_cvt_pk_bf16_f32 v36, v36, v37
	v_cvt_pk_bf16_f32 v37, v38, v39
	global_store_dwordx2 v[44:45], v[36:37], off
	s_nop 0
	v_mul_lo_u32 v0, v46, s13
	v_lshl_add_u64 v[36:37], v[0:1], 1, s[8:9]
	v_lshl_add_u64 v[36:37], v[36:37], 0, v[142:143]
	global_load_dwordx2 v[38:39], v[36:37], off
	global_load_dwordx2 v[198:199], v[36:37], off offset:32
	global_load_dwordx2 v[200:201], v[36:37], off offset:256
	global_load_dwordx2 v[202:203], v[36:37], off offset:288
	v_lshlrev_b32_e32 v44, 10, v46
	s_waitcnt vmcnt(3)
	v_lshlrev_b32_e32 v0, 16, v38
	v_and_b32_e32 v38, 0xffff0000, v38
	v_lshlrev_b32_e32 v40, 16, v39
	v_and_b32_e32 v39, 0xffff0000, v39
	v_mul_f32_e32 v0, 0xbfb8aa3b, v0
	v_mul_f32_e32 v38, 0xbfb8aa3b, v38
	v_mul_f32_e32 v40, 0xbfb8aa3b, v40
	v_mul_f32_e32 v39, 0xbfb8aa3b, v39
	v_exp_f32_e32 v0, v0
	v_exp_f32_e32 v38, v38
	v_exp_f32_e32 v40, v40
	v_exp_f32_e32 v39, v39
	v_min_f32_e32 v0, 0x7149f2ca, v0
	v_min_f32_e32 v38, 0x7149f2ca, v38
	v_min_f32_e32 v40, 0x7149f2ca, v40
	v_min_f32_e32 v39, 0x7149f2ca, v39
	v_add_f32_e32 v0, 1.0, v0
	v_add_f32_e32 v41, 1.0, v38
	v_add_f32_e32 v40, 1.0, v40
	v_add_f32_e32 v42, 1.0, v39
	v_rcp_f32_e32 v38, v0
	v_rcp_f32_e32 v39, v41
	v_rcp_f32_e32 v40, v40
	v_rcp_f32_e32 v41, v42
	v_add_u32_e32 v0, v44, v2
	v_pk_mul_f32 v[32:33], v[32:33], v[38:39]
	v_lshl_add_u64 v[42:43], v[0:1], 1, s[2:3]
	v_pk_mul_f32 v[34:35], v[34:35], v[40:41]
	v_cvt_pk_bf16_f32 v32, v32, v33
	v_cvt_pk_bf16_f32 v33, v34, v35
	global_store_dwordx2 v[42:43], v[32:33], off
	s_nop 0
	s_waitcnt vmcnt(3)
	v_lshlrev_b32_e32 v0, 16, v198
	v_and_b32_e32 v32, 0xffff0000, v198
	v_lshlrev_b32_e32 v34, 16, v199
	v_and_b32_e32 v33, 0xffff0000, v199
	v_mul_f32_e32 v0, 0xbfb8aa3b, v0
	v_mul_f32_e32 v32, 0xbfb8aa3b, v32
	v_mul_f32_e32 v34, 0xbfb8aa3b, v34
	v_mul_f32_e32 v33, 0xbfb8aa3b, v33
	v_exp_f32_e32 v0, v0
	v_exp_f32_e32 v32, v32
	v_exp_f32_e32 v34, v34
	v_exp_f32_e32 v33, v33
	v_min_f32_e32 v0, 0x7149f2ca, v0
	v_min_f32_e32 v32, 0x7149f2ca, v32
	v_min_f32_e32 v34, 0x7149f2ca, v34
	v_min_f32_e32 v33, 0x7149f2ca, v33
	v_add_f32_e32 v0, 1.0, v0
	v_add_f32_e32 v35, 1.0, v32
	v_add_f32_e32 v34, 1.0, v34
	v_add_f32_e32 v38, 1.0, v33
	v_rcp_f32_e32 v32, v0
	v_rcp_f32_e32 v33, v35
	v_rcp_f32_e32 v34, v34
	v_rcp_f32_e32 v35, v38
	v_add_u32_e32 v0, v44, v3
	v_pk_mul_f32 v[28:29], v[28:29], v[32:33]
	v_lshl_add_u64 v[38:39], v[0:1], 1, s[2:3]
	v_pk_mul_f32 v[30:31], v[30:31], v[34:35]
	v_cvt_pk_bf16_f32 v28, v28, v29
	v_cvt_pk_bf16_f32 v29, v30, v31
	global_store_dwordx2 v[38:39], v[28:29], off
	s_nop 0
	s_waitcnt vmcnt(3)
	v_lshlrev_b32_e32 v0, 16, v200
	v_and_b32_e32 v28, 0xffff0000, v200
	v_lshlrev_b32_e32 v30, 16, v201
	v_and_b32_e32 v29, 0xffff0000, v201
	v_mul_f32_e32 v0, 0xbfb8aa3b, v0
	v_mul_f32_e32 v28, 0xbfb8aa3b, v28
	v_mul_f32_e32 v30, 0xbfb8aa3b, v30
	v_mul_f32_e32 v29, 0xbfb8aa3b, v29
	v_exp_f32_e32 v0, v0
	v_exp_f32_e32 v28, v28
	v_exp_f32_e32 v30, v30
	v_exp_f32_e32 v29, v29
	v_min_f32_e32 v0, 0x7149f2ca, v0
	v_min_f32_e32 v28, 0x7149f2ca, v28
	v_min_f32_e32 v30, 0x7149f2ca, v30
	v_min_f32_e32 v29, 0x7149f2ca, v29
	v_add_f32_e32 v0, 1.0, v0
	v_add_f32_e32 v31, 1.0, v28
	v_add_f32_e32 v30, 1.0, v30
	v_add_f32_e32 v32, 1.0, v29
	v_rcp_f32_e32 v28, v0
	v_rcp_f32_e32 v29, v31
	v_rcp_f32_e32 v30, v30
	v_rcp_f32_e32 v31, v32
	v_add_u32_e32 v0, v44, v124
	v_pk_mul_f32 v[24:25], v[24:25], v[28:29]
	v_lshl_add_u64 v[32:33], v[0:1], 1, s[2:3]
	v_pk_mul_f32 v[26:27], v[26:27], v[30:31]
	v_cvt_pk_bf16_f32 v24, v24, v25
	v_cvt_pk_bf16_f32 v25, v26, v27
	global_store_dwordx2 v[32:33], v[24:25], off
	s_nop 0
	v_add_u32_e32 v30, 0xb0, v151
	s_waitcnt vmcnt(3)
	v_lshlrev_b32_e32 v0, 16, v202
	v_and_b32_e32 v24, 0xffff0000, v202
	v_lshlrev_b32_e32 v26, 16, v203
	v_and_b32_e32 v25, 0xffff0000, v203
	v_mul_f32_e32 v0, 0xbfb8aa3b, v0
	v_mul_f32_e32 v24, 0xbfb8aa3b, v24
	v_mul_f32_e32 v26, 0xbfb8aa3b, v26
	v_mul_f32_e32 v25, 0xbfb8aa3b, v25
	v_exp_f32_e32 v0, v0
	v_exp_f32_e32 v24, v24
	v_exp_f32_e32 v26, v26
	v_exp_f32_e32 v25, v25
	v_min_f32_e32 v0, 0x7149f2ca, v0
	v_min_f32_e32 v24, 0x7149f2ca, v24
	v_min_f32_e32 v26, 0x7149f2ca, v26
	v_min_f32_e32 v25, 0x7149f2ca, v25
	v_add_f32_e32 v0, 1.0, v0
	v_add_f32_e32 v27, 1.0, v24
	v_add_f32_e32 v26, 1.0, v26
	v_add_f32_e32 v28, 1.0, v25
	v_rcp_f32_e32 v24, v0
	v_rcp_f32_e32 v25, v27
	v_rcp_f32_e32 v26, v26
	v_rcp_f32_e32 v27, v28
	v_add_u32_e32 v0, v44, v120
	v_pk_mul_f32 v[20:21], v[20:21], v[24:25]
	v_lshl_add_u64 v[28:29], v[0:1], 1, s[2:3]
	v_pk_mul_f32 v[22:23], v[22:23], v[26:27]
	v_cvt_pk_bf16_f32 v20, v20, v21
	v_cvt_pk_bf16_f32 v21, v22, v23
	global_store_dwordx2 v[28:29], v[20:21], off
	s_nop 0
	v_mul_lo_u32 v0, v30, s13
	v_lshl_add_u64 v[20:21], v[0:1], 1, s[8:9]
	v_lshl_add_u64 v[20:21], v[20:21], 0, v[142:143]
	global_load_dwordx2 v[22:23], v[20:21], off
	global_load_dwordx2 v[198:199], v[20:21], off offset:32
	global_load_dwordx2 v[200:201], v[20:21], off offset:256
	global_load_dwordx2 v[202:203], v[20:21], off offset:288
	v_lshlrev_b32_e32 v28, 10, v30
	s_waitcnt vmcnt(3)
	v_lshlrev_b32_e32 v0, 16, v22
	v_and_b32_e32 v22, 0xffff0000, v22
	v_lshlrev_b32_e32 v24, 16, v23
	v_and_b32_e32 v23, 0xffff0000, v23
	v_mul_f32_e32 v0, 0xbfb8aa3b, v0
	v_mul_f32_e32 v22, 0xbfb8aa3b, v22
	v_mul_f32_e32 v24, 0xbfb8aa3b, v24
	v_mul_f32_e32 v23, 0xbfb8aa3b, v23
	v_exp_f32_e32 v0, v0
	v_exp_f32_e32 v22, v22
	v_exp_f32_e32 v24, v24
	v_exp_f32_e32 v23, v23
	v_min_f32_e32 v0, 0x7149f2ca, v0
	v_min_f32_e32 v22, 0x7149f2ca, v22
	v_min_f32_e32 v24, 0x7149f2ca, v24
	v_min_f32_e32 v23, 0x7149f2ca, v23
	v_add_f32_e32 v0, 1.0, v0
	v_add_f32_e32 v25, 1.0, v22
	v_add_f32_e32 v24, 1.0, v24
	v_add_f32_e32 v26, 1.0, v23
	v_rcp_f32_e32 v22, v0
	v_rcp_f32_e32 v23, v25
	v_rcp_f32_e32 v24, v24
	v_rcp_f32_e32 v25, v26
	v_add_u32_e32 v0, v28, v2
	v_pk_mul_f32 v[16:17], v[16:17], v[22:23]
	v_lshl_add_u64 v[26:27], v[0:1], 1, s[2:3]
	v_pk_mul_f32 v[18:19], v[18:19], v[24:25]
	v_cvt_pk_bf16_f32 v16, v16, v17
	v_cvt_pk_bf16_f32 v17, v18, v19
	global_store_dwordx2 v[26:27], v[16:17], off
	s_nop 0
	s_waitcnt vmcnt(3)
	v_lshlrev_b32_e32 v0, 16, v198
	v_and_b32_e32 v2, 0xffff0000, v198
	v_lshlrev_b32_e32 v16, 16, v199
	v_and_b32_e32 v17, 0xffff0000, v199
	v_mul_f32_e32 v0, 0xbfb8aa3b, v0
	v_mul_f32_e32 v2, 0xbfb8aa3b, v2
	v_mul_f32_e32 v16, 0xbfb8aa3b, v16
	v_mul_f32_e32 v17, 0xbfb8aa3b, v17
	v_exp_f32_e32 v0, v0
	v_exp_f32_e32 v2, v2
	v_exp_f32_e32 v16, v16
	v_exp_f32_e32 v17, v17
	v_min_f32_e32 v0, 0x7149f2ca, v0
	v_min_f32_e32 v2, 0x7149f2ca, v2
	v_min_f32_e32 v16, 0x7149f2ca, v16
	v_min_f32_e32 v17, 0x7149f2ca, v17
	v_add_f32_e32 v0, 1.0, v0
	v_add_f32_e32 v2, 1.0, v2
	v_add_f32_e32 v18, 1.0, v16
	v_add_f32_e32 v19, 1.0, v17
	v_rcp_f32_e32 v16, v0
	v_rcp_f32_e32 v17, v2
	v_rcp_f32_e32 v18, v18
	v_rcp_f32_e32 v19, v19
	v_add_u32_e32 v0, v28, v3
	v_pk_mul_f32 v[12:13], v[12:13], v[16:17]
	v_lshl_add_u64 v[2:3], v[0:1], 1, s[2:3]
	v_pk_mul_f32 v[14:15], v[14:15], v[18:19]
	v_cvt_pk_bf16_f32 v12, v12, v13
	v_cvt_pk_bf16_f32 v13, v14, v15
	global_store_dwordx2 v[2:3], v[12:13], off
	s_nop 0
	s_waitcnt vmcnt(3)
	v_lshlrev_b32_e32 v0, 16, v200
	v_and_b32_e32 v2, 0xffff0000, v200
	v_lshlrev_b32_e32 v12, 16, v201
	v_and_b32_e32 v3, 0xffff0000, v201
	v_mul_f32_e32 v0, 0xbfb8aa3b, v0
	v_mul_f32_e32 v2, 0xbfb8aa3b, v2
	v_mul_f32_e32 v12, 0xbfb8aa3b, v12
	v_mul_f32_e32 v3, 0xbfb8aa3b, v3
	v_exp_f32_e32 v0, v0
	v_exp_f32_e32 v2, v2
	v_exp_f32_e32 v12, v12
	v_exp_f32_e32 v3, v3
	v_min_f32_e32 v0, 0x7149f2ca, v0
	v_min_f32_e32 v2, 0x7149f2ca, v2
	v_min_f32_e32 v12, 0x7149f2ca, v12
	v_min_f32_e32 v3, 0x7149f2ca, v3
	v_add_f32_e32 v0, 1.0, v0
	v_add_f32_e32 v13, 1.0, v2
	v_add_f32_e32 v12, 1.0, v12
	v_add_f32_e32 v14, 1.0, v3
	v_rcp_f32_e32 v2, v0
	v_rcp_f32_e32 v3, v13
	v_rcp_f32_e32 v12, v12
	v_rcp_f32_e32 v13, v14
	v_add_u32_e32 v0, v28, v124
	v_pk_mul_f32 v[2:3], v[8:9], v[2:3]
	v_lshl_add_u64 v[14:15], v[0:1], 1, s[2:3]
	v_pk_mul_f32 v[8:9], v[10:11], v[12:13]
	v_cvt_pk_bf16_f32 v2, v2, v3
	v_cvt_pk_bf16_f32 v3, v8, v9
	global_store_dwordx2 v[14:15], v[2:3], off
	s_nop 0
	s_waitcnt vmcnt(3)
	v_lshlrev_b32_e32 v0, 16, v202
	v_and_b32_e32 v2, 0xffff0000, v202
	v_lshlrev_b32_e32 v8, 16, v203
	v_and_b32_e32 v3, 0xffff0000, v203
	v_mul_f32_e32 v0, 0xbfb8aa3b, v0
	v_mul_f32_e32 v2, 0xbfb8aa3b, v2
	v_mul_f32_e32 v8, 0xbfb8aa3b, v8
	v_mul_f32_e32 v3, 0xbfb8aa3b, v3
	v_exp_f32_e32 v0, v0
	v_exp_f32_e32 v2, v2
	v_exp_f32_e32 v8, v8
	v_exp_f32_e32 v3, v3
	v_min_f32_e32 v0, 0x7149f2ca, v0
	v_min_f32_e32 v2, 0x7149f2ca, v2
	v_min_f32_e32 v8, 0x7149f2ca, v8
	v_min_f32_e32 v3, 0x7149f2ca, v3
	v_add_f32_e32 v0, 1.0, v0
	v_add_f32_e32 v9, 1.0, v2
	v_add_f32_e32 v8, 1.0, v8
	v_add_f32_e32 v10, 1.0, v3
	v_rcp_f32_e32 v2, v0
	v_rcp_f32_e32 v3, v9
	v_rcp_f32_e32 v8, v8
	v_rcp_f32_e32 v9, v10
	v_add_u32_e32 v0, v28, v120
	v_pk_mul_f32 v[2:3], v[4:5], v[2:3]
	v_lshl_add_u64 v[10:11], v[0:1], 1, s[2:3]
	v_pk_mul_f32 v[4:5], v[6:7], v[8:9]
	v_cvt_pk_bf16_f32 v2, v2, v3
	v_cvt_pk_bf16_f32 v3, v4, v5
	global_store_dwordx2 v[10:11], v[2:3], off
	s_cbranch_vccnz .LBB0_1071
	s_andn2_b64 vcc, exec, s[0:1]
	s_cbranch_vccnz .LBB0_1070
	s_barrier
	s_branch .LBB0_1070
